# static priority (doc 7.4): per-segment s_setprio flips deleted in the five K-loops, waves 4-7 raised to priority 1 for the duration of each K-loop
# speedup vs baseline: 1.0105x; 1.0077x over previous
_Z3fwdILb1EEv4Args:
	s_load_dwordx4 s[76:79], s[0:1], 0x88
	s_load_dword s73, s[0:1], 0x98
	s_mov_b32 s69, s2
	s_add_u32 s2, s0, 0x98
	v_writelane_b32 v254, s0, 0
	s_addc_u32 s3, s1, 0
	v_and_b32_e32 v214, 0x3ff, v0
	s_nop 0
	v_readfirstlane_b32 s99, v214
	s_lshr_b32 s99, s99, 8
	v_writelane_b32 v254, s1, 1
	v_writelane_b32 v254, s2, 2
	v_cmp_gt_u32_e32 vcc, 2, v214
	s_nop 0
	v_writelane_b32 v254, s3, 3
	s_and_saveexec_b64 s[0:1], vcc
	v_lshl_add_u32 v1, v214, 2, 0
	v_add_u32_e32 v1, 0x23fc0, v1
	v_mov_b32_e32 v2, 0
	ds_write_b32 v1, v2
	s_or_b64 exec, exec, s[0:1]
	s_waitcnt lgkmcnt(0)
	s_add_u32 s2, s76, 0x10000
	s_barrier
	s_getreg_b32 s0, hwreg(HW_REG_XCC_ID, 0, 4)
	s_addc_u32 s3, s77, 0
	s_and_b32 s48, s0, 15
	v_cmp_eq_u32_e64 s[4:5], 0, v214
	s_mov_b64 s[0:1], exec
	s_nop 0
	v_writelane_b32 v254, s4, 4
	s_nop 1
	v_writelane_b32 v254, s5, 5
	s_and_b64 s[4:5], s[0:1], s[4:5]
	s_mov_b64 exec, s[4:5]
	s_cbranch_execz .LBB0_5
	s_mov_b64 s[4:5], exec
	v_mbcnt_lo_u32_b32 v1, s4, 0
	v_mbcnt_hi_u32_b32 v1, s5, v1
	v_cmp_eq_u32_e32 vcc, 0, v1
	s_and_b64 s[6:7], exec, vcc
	s_mov_b64 exec, s[6:7]
	s_cbranch_execz .LBB0_5
	s_lshl_b32 s6, s48, 8
	s_bcnt1_i32_b64 s4, s[4:5]
	v_mov_b32_e32 v1, s6
	v_mov_b32_e32 v2, s4
	global_atomic_add v1, v2, s[2:3] offset:1024

.LBB0_169:
	s_ashr_i32 s51, s50, 31
	s_lshl_b64 s[12:13], s[50:51], 19
	s_add_u32 s52, s17, s12
	s_addc_u32 s53, s60, s13
	s_and_b64 s[12:13], s[40:41], exec
	s_cselect_b32 s3, s53, s9
	s_cselect_b32 s24, s52, s8
	s_ashr_i32 s49, s48, 31
	s_lshl_b64 s[12:13], s[48:49], 19
	s_add_u32 s54, s82, s12
	s_addc_u32 s55, s83, s13
	s_and_b64 s[12:13], s[40:41], exec
	s_cselect_b32 s25, s55, s11
	s_cselect_b32 s26, s54, s10
	s_add_u32 s8, s8, 0x40080
	s_addc_u32 s9, s9, 0
	s_add_u32 s27, s10, 0x100
	v_mov_b32_e32 v2, 0
	s_addc_u32 s28, s11, 0
	s_mov_b32 s29, -2
	v_mov_b64_e32 v[2:3], 0
	v_mov_b64_e32 v[4:5], 0
	v_mov_b64_e32 v[6:7], 0
	v_mov_b64_e32 v[8:9], 0
	v_mov_b64_e32 v[10:11], 0
	v_mov_b64_e32 v[12:13], 0
	v_mov_b64_e32 v[14:15], 0
	v_mov_b64_e32 v[16:17], 0
	v_mov_b64_e32 v[18:19], 0
	v_mov_b64_e32 v[20:21], 0
	v_mov_b64_e32 v[22:23], 0
	v_mov_b64_e32 v[24:25], 0
	v_mov_b64_e32 v[26:27], 0
	v_mov_b64_e32 v[28:29], 0
	v_mov_b64_e32 v[30:31], 0
	v_mov_b64_e32 v[32:33], 0
	v_mov_b64_e32 v[34:35], 0
	v_mov_b64_e32 v[36:37], 0
	v_mov_b64_e32 v[38:39], 0
	v_mov_b64_e32 v[40:41], 0
	v_mov_b64_e32 v[42:43], 0
	v_mov_b64_e32 v[44:45], 0
	v_mov_b64_e32 v[46:47], 0
	v_mov_b64_e32 v[48:49], 0
	v_mov_b64_e32 v[50:51], 0
	v_mov_b64_e32 v[52:53], 0
	v_mov_b64_e32 v[54:55], 0
	v_mov_b64_e32 v[56:57], 0
	v_mov_b64_e32 v[58:59], 0
	v_mov_b64_e32 v[60:61], 0
	v_mov_b64_e32 v[62:63], 0
	v_mov_b64_e32 v[64:65], 0
	v_mov_b64_e32 v[66:67], 0
	v_mov_b64_e32 v[68:69], 0
	v_mov_b64_e32 v[70:71], 0
	v_mov_b64_e32 v[72:73], 0
	v_mov_b64_e32 v[74:75], 0
	v_mov_b64_e32 v[76:77], 0
	v_mov_b64_e32 v[78:79], 0
	v_mov_b64_e32 v[80:81], 0
	v_mov_b64_e32 v[82:83], 0
	v_mov_b64_e32 v[84:85], 0
	v_mov_b64_e32 v[86:87], 0
	v_mov_b64_e32 v[88:89], 0
	v_mov_b64_e32 v[90:91], 0
	v_mov_b64_e32 v[92:93], 0
	v_mov_b64_e32 v[94:95], 0
	v_mov_b64_e32 v[96:97], 0
	v_mov_b64_e32 v[98:99], 0
	v_mov_b64_e32 v[100:101], 0
	v_mov_b64_e32 v[102:103], 0
	v_mov_b64_e32 v[104:105], 0
	v_mov_b64_e32 v[106:107], 0
	v_mov_b64_e32 v[108:109], 0
	v_mov_b64_e32 v[110:111], 0
	v_mov_b64_e32 v[112:113], 0
	v_mov_b64_e32 v[114:115], 0
	v_mov_b64_e32 v[116:117], 0
	v_mov_b64_e32 v[118:119], 0
	v_mov_b64_e32 v[120:121], 0
	v_mov_b64_e32 v[122:123], 0
	v_mov_b64_e32 v[124:125], 0
	v_mov_b64_e32 v[126:127], 0
	v_mov_b64_e32 v[128:129], 0
	s_cmp_eq_u32 s99, 1
	s_cbranch_scc0 .Lprio_LBB0_170
	s_setprio 1
.Lprio_LBB0_170:
.LBB0_170:
	s_add_u32 s10, s8, 0xfffc0080
	s_addc_u32 s11, s9, -1
	s_add_i32 s30, 0, 0x10000
	s_cmp_eq_u32 s29, 12
	s_cselect_b32 s13, s3, s11
	s_cselect_b32 s12, s24, s10
	s_cselect_b32 s11, s25, s28
	s_cselect_b32 s10, s26, s27
	s_add_i32 s31, 0, 0x14000
	.p2align	8
.Lk1_body:
	v_add_u32_e32 v0, s30, v197
	ds_read_b128 v[130:133], v0
	ds_read_b128 v[134:137], v0 offset:1024
	ds_read_b128 v[138:141], v0 offset:2048
	ds_read_b128 v[142:145], v0 offset:3072
	v_add_u32_e32 v0, s31, v197
	ds_read_b128 v[170:173], v0
	ds_read_b128 v[174:177], v0 offset:1024
	ds_read_b128 v[202:205], v0 offset:2048
	ds_read_b128 v[206:209], v0 offset:3072
	s_add_i32 m0, s59, 0xc000
	ds_read_b128 v[210:213], v200
	ds_read_b128 v[216:219], v200 offset:1024
	ds_read_b128 v[220:223], v200 offset:2048
	ds_read_b128 v[224:227], v200 offset:3072
	ds_read_b128 v[228:231], v200 offset:4096
	ds_read_b128 v[232:235], v200 offset:5120
	ds_read_b128 v[236:239], v200 offset:6144
	ds_read_b128 v[240:243], v200 offset:7168
	global_load_lds_dwordx4 v166, s[8:9]
	s_add_i32 m0, s59, 0xe000
	s_nop 0
	global_load_lds_dwordx4 v168, s[8:9]
	s_waitcnt vmcnt(8)
	s_waitcnt lgkmcnt(0)
	s_barrier
	s_waitcnt lgkmcnt(0)
	v_mfma_f32_16x16x32_bf16 v[126:129], v[130:133], v[210:213], v[126:129]
	v_mfma_f32_16x16x32_bf16 v[122:125], v[138:141], v[210:213], v[122:125]
	v_mfma_f32_16x16x32_bf16 v[110:113], v[130:133], v[220:223], v[110:113]
	v_mfma_f32_16x16x32_bf16 v[106:109], v[138:141], v[220:223], v[106:109]
	v_mfma_f32_16x16x32_bf16 v[94:97], v[130:133], v[228:231], v[94:97]
	v_mfma_f32_16x16x32_bf16 v[90:93], v[138:141], v[228:231], v[90:93]
	v_mfma_f32_16x16x32_bf16 v[78:81], v[130:133], v[236:239], v[78:81]
	v_mfma_f32_16x16x32_bf16 v[74:77], v[138:141], v[236:239], v[74:77]
	v_mfma_f32_16x16x32_bf16 v[126:129], v[134:137], v[216:219], v[126:129]
	v_mfma_f32_16x16x32_bf16 v[122:125], v[142:145], v[216:219], v[122:125]
	v_mfma_f32_16x16x32_bf16 v[110:113], v[134:137], v[224:227], v[110:113]
	v_mfma_f32_16x16x32_bf16 v[106:109], v[142:145], v[224:227], v[106:109]
	v_mfma_f32_16x16x32_bf16 v[94:97], v[134:137], v[232:235], v[94:97]
	v_mfma_f32_16x16x32_bf16 v[90:93], v[142:145], v[232:235], v[90:93]
	v_mfma_f32_16x16x32_bf16 v[78:81], v[134:137], v[240:243], v[78:81]
	v_mfma_f32_16x16x32_bf16 v[74:77], v[142:145], v[240:243], v[74:77]
	v_mfma_f32_16x16x32_bf16 v[118:121], v[170:173], v[210:213], v[118:121]
	v_mfma_f32_16x16x32_bf16 v[114:117], v[202:205], v[210:213], v[114:117]
	v_mfma_f32_16x16x32_bf16 v[102:105], v[170:173], v[220:223], v[102:105]
	v_mfma_f32_16x16x32_bf16 v[98:101], v[202:205], v[220:223], v[98:101]
	v_mfma_f32_16x16x32_bf16 v[86:89], v[170:173], v[228:231], v[86:89]
	v_mfma_f32_16x16x32_bf16 v[82:85], v[202:205], v[228:231], v[82:85]
	v_mfma_f32_16x16x32_bf16 v[70:73], v[170:173], v[236:239], v[70:73]
	v_mfma_f32_16x16x32_bf16 v[66:69], v[202:205], v[236:239], v[66:69]
	v_mfma_f32_16x16x32_bf16 v[118:121], v[174:177], v[216:219], v[118:121]
	v_mfma_f32_16x16x32_bf16 v[114:117], v[206:209], v[216:219], v[114:117]
	v_mfma_f32_16x16x32_bf16 v[102:105], v[174:177], v[224:227], v[102:105]
	v_mfma_f32_16x16x32_bf16 v[98:101], v[206:209], v[224:227], v[98:101]
	v_mfma_f32_16x16x32_bf16 v[86:89], v[174:177], v[232:235], v[86:89]
	v_mfma_f32_16x16x32_bf16 v[82:85], v[206:209], v[232:235], v[82:85]
	v_mfma_f32_16x16x32_bf16 v[70:73], v[174:177], v[240:243], v[70:73]
	v_mfma_f32_16x16x32_bf16 v[66:69], v[206:209], v[240:243], v[66:69]
	s_barrier
	s_add_i32 s30, s30, s61
	s_mov_b32 m0, s30
	ds_read_b128 v[210:213], v200 offset:16384
	ds_read_b128 v[216:219], v200 offset:17408
	ds_read_b128 v[220:223], v200 offset:18432
	ds_read_b128 v[224:227], v200 offset:19456
	ds_read_b128 v[228:231], v200 offset:20480
	ds_read_b128 v[232:235], v200 offset:21504
	ds_read_b128 v[236:239], v200 offset:22528
	ds_read_b128 v[240:243], v200 offset:23552
	global_load_lds_dwordx4 v154, s[10:11]
	s_add_i32 m0, s30, 0x2000
	s_add_u32 s42, s10, 0x40000
	s_addc_u32 s43, s11, 0
	s_add_i32 s30, s31, s61
	global_load_lds_dwordx4 v158, s[10:11]
	s_mov_b32 m0, s30
	s_nop 0
	global_load_lds_dwordx4 v154, s[42:43]
	s_mov_b32 m0, s59
	s_nop 0
	global_load_lds_dwordx4 v152, s[12:13]
	s_mov_b32 m0, s62
	s_nop 0
	global_load_lds_dwordx4 v156, s[12:13]
	s_waitcnt vmcnt(7)
	s_waitcnt lgkmcnt(0)
	s_barrier
	s_waitcnt lgkmcnt(0)
	v_mfma_f32_16x16x32_bf16 v[62:65], v[130:133], v[210:213], v[62:65]
	v_mfma_f32_16x16x32_bf16 v[58:61], v[138:141], v[210:213], v[58:61]
	v_mfma_f32_16x16x32_bf16 v[46:49], v[130:133], v[220:223], v[46:49]
	v_mfma_f32_16x16x32_bf16 v[42:45], v[138:141], v[220:223], v[42:45]
	v_mfma_f32_16x16x32_bf16 v[30:33], v[130:133], v[228:231], v[30:33]
	v_mfma_f32_16x16x32_bf16 v[26:29], v[138:141], v[228:231], v[26:29]
	v_mfma_f32_16x16x32_bf16 v[14:17], v[130:133], v[236:239], v[14:17]
	v_mfma_f32_16x16x32_bf16 v[10:13], v[138:141], v[236:239], v[10:13]
	v_mfma_f32_16x16x32_bf16 v[62:65], v[134:137], v[216:219], v[62:65]
	v_mfma_f32_16x16x32_bf16 v[58:61], v[142:145], v[216:219], v[58:61]
	v_mfma_f32_16x16x32_bf16 v[46:49], v[134:137], v[224:227], v[46:49]
	v_mfma_f32_16x16x32_bf16 v[42:45], v[142:145], v[224:227], v[42:45]
	v_mfma_f32_16x16x32_bf16 v[30:33], v[134:137], v[232:235], v[30:33]
	v_mfma_f32_16x16x32_bf16 v[26:29], v[142:145], v[232:235], v[26:29]
	v_mfma_f32_16x16x32_bf16 v[14:17], v[134:137], v[240:243], v[14:17]
	v_mfma_f32_16x16x32_bf16 v[10:13], v[142:145], v[240:243], v[10:13]
	v_mfma_f32_16x16x32_bf16 v[54:57], v[170:173], v[210:213], v[54:57]
	v_mfma_f32_16x16x32_bf16 v[50:53], v[202:205], v[210:213], v[50:53]
	v_mfma_f32_16x16x32_bf16 v[38:41], v[170:173], v[220:223], v[38:41]
	v_mfma_f32_16x16x32_bf16 v[34:37], v[202:205], v[220:223], v[34:37]
	v_mfma_f32_16x16x32_bf16 v[22:25], v[170:173], v[228:231], v[22:25]
	v_mfma_f32_16x16x32_bf16 v[18:21], v[202:205], v[228:231], v[18:21]
	v_mfma_f32_16x16x32_bf16 v[6:9], v[170:173], v[236:239], v[6:9]
	v_mfma_f32_16x16x32_bf16 v[2:5], v[202:205], v[236:239], v[2:5]
	v_mfma_f32_16x16x32_bf16 v[54:57], v[174:177], v[216:219], v[54:57]
	v_mfma_f32_16x16x32_bf16 v[50:53], v[206:209], v[216:219], v[50:53]
	v_mfma_f32_16x16x32_bf16 v[38:41], v[174:177], v[224:227], v[38:41]
	v_mfma_f32_16x16x32_bf16 v[34:37], v[206:209], v[224:227], v[34:37]
	v_mfma_f32_16x16x32_bf16 v[22:25], v[174:177], v[232:235], v[22:25]
	v_mfma_f32_16x16x32_bf16 v[18:21], v[206:209], v[232:235], v[18:21]
	v_mfma_f32_16x16x32_bf16 v[6:9], v[174:177], v[240:243], v[6:9]
	v_mfma_f32_16x16x32_bf16 v[2:5], v[206:209], v[240:243], v[2:5]
	s_barrier
	s_add_i32 m0, s30, 0x2000
	s_nop 0
	global_load_lds_dwordx4 v158, s[42:43]
	s_add_i32 s30, 0, 0x18000
	v_add_u32_e32 v0, s30, v197
	s_add_i32 s31, 0, 0x1c000
	ds_read_b128 v[130:133], v0
	ds_read_b128 v[134:137], v0 offset:1024
	ds_read_b128 v[138:141], v0 offset:2048
	ds_read_b128 v[142:145], v0 offset:3072
	v_add_u32_e32 v0, s31, v197
	ds_read_b128 v[170:173], v0
	ds_read_b128 v[174:177], v0 offset:1024
	ds_read_b128 v[202:205], v0 offset:2048
	ds_read_b128 v[206:209], v0 offset:3072
	s_add_u32 s12, s12, 0x40000
	s_addc_u32 s13, s13, 0
	s_mov_b32 m0, s63
	ds_read_b128 v[210:213], v200 offset:32768
	ds_read_b128 v[216:219], v200 offset:33792
	ds_read_b128 v[220:223], v200 offset:34816
	ds_read_b128 v[224:227], v200 offset:35840
	ds_read_b128 v[228:231], v200 offset:36864
	ds_read_b128 v[232:235], v200 offset:37888
	ds_read_b128 v[236:239], v200 offset:38912
	ds_read_b128 v[240:243], v200 offset:39936
	global_load_lds_dwordx4 v152, s[12:13]
	s_mov_b32 m0, s64
	s_nop 0
	global_load_lds_dwordx4 v156, s[12:13]
	s_waitcnt vmcnt(8)
	s_waitcnt lgkmcnt(0)
	s_barrier
	s_waitcnt lgkmcnt(0)
	v_mfma_f32_16x16x32_bf16 v[126:129], v[130:133], v[210:213], v[126:129]
	v_mfma_f32_16x16x32_bf16 v[122:125], v[138:141], v[210:213], v[122:125]
	v_mfma_f32_16x16x32_bf16 v[110:113], v[130:133], v[220:223], v[110:113]
	v_mfma_f32_16x16x32_bf16 v[106:109], v[138:141], v[220:223], v[106:109]
	v_mfma_f32_16x16x32_bf16 v[94:97], v[130:133], v[228:231], v[94:97]
	v_mfma_f32_16x16x32_bf16 v[90:93], v[138:141], v[228:231], v[90:93]
	v_mfma_f32_16x16x32_bf16 v[78:81], v[130:133], v[236:239], v[78:81]
	v_mfma_f32_16x16x32_bf16 v[74:77], v[138:141], v[236:239], v[74:77]
	v_mfma_f32_16x16x32_bf16 v[126:129], v[134:137], v[216:219], v[126:129]
	v_mfma_f32_16x16x32_bf16 v[122:125], v[142:145], v[216:219], v[122:125]
	v_mfma_f32_16x16x32_bf16 v[110:113], v[134:137], v[224:227], v[110:113]
	v_mfma_f32_16x16x32_bf16 v[106:109], v[142:145], v[224:227], v[106:109]
	v_mfma_f32_16x16x32_bf16 v[94:97], v[134:137], v[232:235], v[94:97]
	v_mfma_f32_16x16x32_bf16 v[90:93], v[142:145], v[232:235], v[90:93]
	v_mfma_f32_16x16x32_bf16 v[78:81], v[134:137], v[240:243], v[78:81]
	v_mfma_f32_16x16x32_bf16 v[74:77], v[142:145], v[240:243], v[74:77]
	v_mfma_f32_16x16x32_bf16 v[118:121], v[170:173], v[210:213], v[118:121]
	v_mfma_f32_16x16x32_bf16 v[114:117], v[202:205], v[210:213], v[114:117]
	v_mfma_f32_16x16x32_bf16 v[102:105], v[170:173], v[220:223], v[102:105]
	v_mfma_f32_16x16x32_bf16 v[98:101], v[202:205], v[220:223], v[98:101]
	v_mfma_f32_16x16x32_bf16 v[86:89], v[170:173], v[228:231], v[86:89]
	v_mfma_f32_16x16x32_bf16 v[82:85], v[202:205], v[228:231], v[82:85]
	v_mfma_f32_16x16x32_bf16 v[70:73], v[170:173], v[236:239], v[70:73]
	v_mfma_f32_16x16x32_bf16 v[66:69], v[202:205], v[236:239], v[66:69]
	v_mfma_f32_16x16x32_bf16 v[118:121], v[174:177], v[216:219], v[118:121]
	v_mfma_f32_16x16x32_bf16 v[114:117], v[206:209], v[216:219], v[114:117]
	v_mfma_f32_16x16x32_bf16 v[102:105], v[174:177], v[224:227], v[102:105]
	v_mfma_f32_16x16x32_bf16 v[98:101], v[206:209], v[224:227], v[98:101]
	v_mfma_f32_16x16x32_bf16 v[86:89], v[174:177], v[232:235], v[86:89]
	v_mfma_f32_16x16x32_bf16 v[82:85], v[206:209], v[232:235], v[82:85]
	v_mfma_f32_16x16x32_bf16 v[70:73], v[174:177], v[240:243], v[70:73]
	v_mfma_f32_16x16x32_bf16 v[66:69], v[206:209], v[240:243], v[66:69]
	s_barrier
	s_add_i32 m0, s30, s61
	s_add_u32 s42, s10, 0x80
	s_addc_u32 s43, s11, 0
	ds_read_b128 v[210:213], v200 offset:49152
	ds_read_b128 v[216:219], v200 offset:50176
	ds_read_b128 v[220:223], v200 offset:51200
	ds_read_b128 v[224:227], v200 offset:52224
	ds_read_b128 v[228:231], v200 offset:53248
	ds_read_b128 v[232:235], v200 offset:54272
	ds_read_b128 v[236:239], v200 offset:55296
	ds_read_b128 v[240:243], v200 offset:56320
	global_load_lds_dwordx4 v154, s[42:43]
	s_add_i32 m0, m0, 0x2000
	s_add_u32 s10, s10, 0x40080
	s_addc_u32 s11, s11, 0
	global_load_lds_dwordx4 v158, s[42:43]
	s_add_i32 m0, s31, s61
	s_add_u32 s42, s12, 0xfffc0080
	s_addc_u32 s43, s13, -1
	global_load_lds_dwordx4 v154, s[10:11]
	s_add_i32 m0, m0, 0x2000
	s_nop 0
	global_load_lds_dwordx4 v158, s[10:11]
	s_mov_b32 m0, s66
	s_nop 0
	global_load_lds_dwordx4 v152, s[42:43]
	s_mov_b32 m0, s67
	s_add_i32 s12, s31, s61
	global_load_lds_dwordx4 v156, s[42:43]
	s_add_i32 s29, s29, 2
	s_add_u32 s8, s8, 0x100
	s_addc_u32 s9, s9, 0
	s_add_u32 s27, s27, 0x100
	s_addc_u32 s28, s28, 0
	s_cmp_gt_u32 s29, 13
	s_cbranch_scc1 .Lk1_skip
	s_add_u32 s10, s8, 0xfffc0080
	s_addc_u32 s11, s9, -1
	s_add_i32 s30, 0, 0x10000
	s_cmp_eq_u32 s29, 12
	s_cselect_b32 s13, s3, s11
	s_cselect_b32 s12, s24, s10
	s_cselect_b32 s11, s25, s28
	s_cselect_b32 s10, s26, s27
	s_add_i32 s31, 0, 0x14000
.Lk1_skip:
	s_waitcnt vmcnt(8)
	s_waitcnt lgkmcnt(0)
	s_barrier
	s_waitcnt lgkmcnt(0)
	v_mfma_f32_16x16x32_bf16 v[62:65], v[130:133], v[210:213], v[62:65]
	v_mfma_f32_16x16x32_bf16 v[58:61], v[138:141], v[210:213], v[58:61]
	v_mfma_f32_16x16x32_bf16 v[46:49], v[130:133], v[220:223], v[46:49]
	v_mfma_f32_16x16x32_bf16 v[42:45], v[138:141], v[220:223], v[42:45]
	v_mfma_f32_16x16x32_bf16 v[30:33], v[130:133], v[228:231], v[30:33]
	v_mfma_f32_16x16x32_bf16 v[26:29], v[138:141], v[228:231], v[26:29]
	v_mfma_f32_16x16x32_bf16 v[14:17], v[130:133], v[236:239], v[14:17]
	v_mfma_f32_16x16x32_bf16 v[10:13], v[138:141], v[236:239], v[10:13]
	v_mfma_f32_16x16x32_bf16 v[62:65], v[134:137], v[216:219], v[62:65]
	v_mfma_f32_16x16x32_bf16 v[58:61], v[142:145], v[216:219], v[58:61]
	v_mfma_f32_16x16x32_bf16 v[46:49], v[134:137], v[224:227], v[46:49]
	v_mfma_f32_16x16x32_bf16 v[42:45], v[142:145], v[224:227], v[42:45]
	v_mfma_f32_16x16x32_bf16 v[30:33], v[134:137], v[232:235], v[30:33]
	v_mfma_f32_16x16x32_bf16 v[26:29], v[142:145], v[232:235], v[26:29]
	v_mfma_f32_16x16x32_bf16 v[14:17], v[134:137], v[240:243], v[14:17]
	v_mfma_f32_16x16x32_bf16 v[10:13], v[142:145], v[240:243], v[10:13]
	v_mfma_f32_16x16x32_bf16 v[54:57], v[170:173], v[210:213], v[54:57]
	v_mfma_f32_16x16x32_bf16 v[50:53], v[202:205], v[210:213], v[50:53]
	v_mfma_f32_16x16x32_bf16 v[38:41], v[170:173], v[220:223], v[38:41]
	v_mfma_f32_16x16x32_bf16 v[34:37], v[202:205], v[220:223], v[34:37]
	v_mfma_f32_16x16x32_bf16 v[22:25], v[170:173], v[228:231], v[22:25]
	v_mfma_f32_16x16x32_bf16 v[18:21], v[202:205], v[228:231], v[18:21]
	v_mfma_f32_16x16x32_bf16 v[6:9], v[170:173], v[236:239], v[6:9]
	v_mfma_f32_16x16x32_bf16 v[2:5], v[202:205], v[236:239], v[2:5]
	v_mfma_f32_16x16x32_bf16 v[54:57], v[174:177], v[216:219], v[54:57]
	v_mfma_f32_16x16x32_bf16 v[50:53], v[206:209], v[216:219], v[50:53]
	v_mfma_f32_16x16x32_bf16 v[38:41], v[174:177], v[224:227], v[38:41]
	v_mfma_f32_16x16x32_bf16 v[34:37], v[206:209], v[224:227], v[34:37]
	v_mfma_f32_16x16x32_bf16 v[22:25], v[174:177], v[232:235], v[22:25]
	v_mfma_f32_16x16x32_bf16 v[18:21], v[206:209], v[232:235], v[18:21]
	v_mfma_f32_16x16x32_bf16 v[6:9], v[174:177], v[240:243], v[6:9]
	v_mfma_f32_16x16x32_bf16 v[2:5], v[206:209], v[240:243], v[2:5]
	s_barrier
	s_cmp_gt_u32 s29, 13
	s_cbranch_scc0 .Lk1_body
	s_setprio 0
	s_and_b64 vcc, exec, s[46:47]
	s_cbranch_vccz .LBB0_173
	s_barrier

.LBB0_545:
	s_ashr_i32 s47, s46, 31
	s_lshl_b64 s[14:15], s[46:47], 19
	s_add_u32 s48, s74, s14
	s_addc_u32 s49, s75, s15
	s_and_b64 s[14:15], s[40:41], exec
	s_cselect_b32 s14, s49, s53
	s_cselect_b32 s15, s48, s52
	s_ashr_i32 s45, s44, 31
	s_lshl_b64 s[24:25], s[44:45], 19
	s_add_u32 s50, s0, s24
	s_addc_u32 s51, s1, s25
	s_and_b64 s[24:25], s[40:41], exec
	s_cselect_b32 s26, s51, s11
	s_cselect_b32 s27, s50, s10
	s_lshl_b32 s24, s12, 8
	s_lshl_b32 s25, s13, 8
	s_or_b32 s28, s25, s63
	s_add_i32 s29, s24, s62
	s_add_u32 s12, s52, 0x40080
	s_addc_u32 s13, s53, 0
	v_mov_b32_e32 v2, v1
	v_mov_b32_e32 v3, v1
	s_add_u32 s45, s10, 0x100
	v_mov_b32_e32 v0, v1
	v_mov_b64_e32 v[6:7], v[2:3]
	v_mov_b64_e32 v[10:11], v[2:3]
	v_mov_b64_e32 v[22:23], v[2:3]
	v_mov_b64_e32 v[26:27], v[2:3]
	v_mov_b64_e32 v[38:39], v[2:3]
	v_mov_b64_e32 v[42:43], v[2:3]
	v_mov_b64_e32 v[54:55], v[2:3]
	v_mov_b64_e32 v[58:59], v[2:3]
	v_mov_b64_e32 v[14:15], v[2:3]
	v_mov_b64_e32 v[18:19], v[2:3]
	v_mov_b64_e32 v[30:31], v[2:3]
	v_mov_b64_e32 v[34:35], v[2:3]
	v_mov_b64_e32 v[46:47], v[2:3]
	v_mov_b64_e32 v[50:51], v[2:3]
	v_mov_b64_e32 v[62:63], v[2:3]
	v_mov_b64_e32 v[66:67], v[2:3]
	v_mov_b64_e32 v[70:71], v[2:3]
	v_mov_b64_e32 v[74:75], v[2:3]
	v_mov_b64_e32 v[86:87], v[2:3]
	v_mov_b64_e32 v[90:91], v[2:3]
	v_mov_b64_e32 v[102:103], v[2:3]
	v_mov_b64_e32 v[106:107], v[2:3]
	v_mov_b64_e32 v[118:119], v[2:3]
	v_mov_b64_e32 v[122:123], v[2:3]
	v_mov_b64_e32 v[78:79], v[2:3]
	v_mov_b64_e32 v[82:83], v[2:3]
	v_mov_b64_e32 v[94:95], v[2:3]
	v_mov_b64_e32 v[98:99], v[2:3]
	v_mov_b64_e32 v[110:111], v[2:3]
	v_mov_b64_e32 v[114:115], v[2:3]
	v_mov_b64_e32 v[126:127], v[2:3]
	v_mov_b64_e32 v[130:131], v[2:3]
	v_lshl_add_u64 v[154:155], s[12:13], 0, v[144:145]
	v_lshl_add_u64 v[156:157], s[12:13], 0, v[152:153]
	s_addc_u32 s47, s11, 0
	s_mov_b32 s68, -2
	s_mov_b64 s[10:11], 0
	v_mov_b64_e32 v[4:5], v[0:1]
	v_mov_b64_e32 v[8:9], v[0:1]
	v_mov_b64_e32 v[20:21], v[0:1]
	v_mov_b64_e32 v[24:25], v[0:1]
	v_mov_b64_e32 v[36:37], v[0:1]
	v_mov_b64_e32 v[40:41], v[0:1]
	v_mov_b64_e32 v[52:53], v[0:1]
	v_mov_b64_e32 v[56:57], v[0:1]
	v_mov_b64_e32 v[12:13], v[0:1]
	v_mov_b64_e32 v[16:17], v[0:1]
	v_mov_b64_e32 v[28:29], v[0:1]
	v_mov_b64_e32 v[32:33], v[0:1]
	v_mov_b64_e32 v[44:45], v[0:1]
	v_mov_b64_e32 v[48:49], v[0:1]
	v_mov_b64_e32 v[60:61], v[0:1]
	v_mov_b64_e32 v[64:65], v[0:1]
	v_mov_b64_e32 v[68:69], v[0:1]
	v_mov_b64_e32 v[72:73], v[0:1]
	v_mov_b64_e32 v[84:85], v[0:1]
	v_mov_b64_e32 v[88:89], v[0:1]
	v_mov_b64_e32 v[100:101], v[0:1]
	v_mov_b64_e32 v[104:105], v[0:1]
	v_mov_b64_e32 v[116:117], v[0:1]
	v_mov_b64_e32 v[120:121], v[0:1]
	v_mov_b64_e32 v[76:77], v[0:1]
	v_mov_b64_e32 v[80:81], v[0:1]
	v_mov_b64_e32 v[92:93], v[0:1]
	v_mov_b64_e32 v[96:97], v[0:1]
	v_mov_b64_e32 v[108:109], v[0:1]
	v_mov_b64_e32 v[112:113], v[0:1]
	v_mov_b64_e32 v[124:125], v[0:1]
	v_mov_b64_e32 v[128:129], v[0:1]
	s_cmp_eq_u32 s99, 1
	s_cbranch_scc0 .Lprio_LBB0_546
	s_setprio 1
.Lprio_LBB0_546:
	s_branch .LBB0_547
.LBB0_546:
	s_add_u32 s12, s52, s10
	s_addc_u32 s13, s53, s11
	s_add_u32 s12, s12, 0x100
	s_addc_u32 s13, s13, 0
	s_add_u32 s30, s45, s10
	s_addc_u32 s31, s47, s11
	s_cmpk_eq_i32 s10, 0x700
	s_cselect_b32 s55, s14, s13
	s_cselect_b32 s54, s15, s12
	s_cselect_b32 s13, s26, s31
	s_cselect_b32 s12, s27, s30
	s_add_i32 s30, 0, 0x10000
	v_add_u32_e32 v0, s30, v160
	s_add_i32 s34, 0, 0x14000
	ds_read_b128 v[132:135], v0
	ds_read_b128 v[164:167], v0 offset:1024
	ds_read_b128 v[168:171], v0 offset:2048
	ds_read_b128 v[172:175], v0 offset:3072
	v_add_u32_e32 v0, s34, v160
	ds_read_b128 v[198:201], v0
	ds_read_b128 v[202:205], v0 offset:1024
	ds_read_b128 v[206:209], v0 offset:2048
	ds_read_b128 v[210:213], v0 offset:3072
	v_lshl_add_u64 v[2:3], v[154:155], 0, s[10:11]
	s_add_i32 m0, s58, 0xc000
	ds_read_b128 v[216:219], v163
	ds_read_b128 v[220:223], v163 offset:1024
	ds_read_b128 v[224:227], v163 offset:2048
	ds_read_b128 v[228:231], v163 offset:3072
	ds_read_b128 v[232:235], v163 offset:4096
	ds_read_b128 v[236:239], v163 offset:5120
	ds_read_b128 v[240:243], v163 offset:6144
	ds_read_b128 v[244:247], v163 offset:7168
	global_load_lds_dwordx4 v[2:3], off
	v_lshl_add_u64 v[2:3], v[156:157], 0, s[10:11]
	s_add_i32 m0, s58, 0xe000
	s_nop 0
	global_load_lds_dwordx4 v[2:3], off
	s_waitcnt vmcnt(8)
	s_waitcnt lgkmcnt(0)
	s_barrier
	s_waitcnt lgkmcnt(0)
	v_mfma_f32_16x16x32_bf16 v[128:131], v[132:135], v[216:219], v[128:131]
	v_mfma_f32_16x16x32_bf16 v[124:127], v[168:171], v[216:219], v[124:127]
	v_mfma_f32_16x16x32_bf16 v[112:115], v[132:135], v[224:227], v[112:115]
	v_mfma_f32_16x16x32_bf16 v[108:111], v[168:171], v[224:227], v[108:111]
	v_mfma_f32_16x16x32_bf16 v[96:99], v[132:135], v[232:235], v[96:99]
	v_mfma_f32_16x16x32_bf16 v[92:95], v[168:171], v[232:235], v[92:95]
	v_mfma_f32_16x16x32_bf16 v[80:83], v[132:135], v[240:243], v[80:83]
	v_mfma_f32_16x16x32_bf16 v[76:79], v[168:171], v[240:243], v[76:79]
	v_mfma_f32_16x16x32_bf16 v[128:131], v[164:167], v[220:223], v[128:131]
	v_mfma_f32_16x16x32_bf16 v[124:127], v[172:175], v[220:223], v[124:127]
	v_mfma_f32_16x16x32_bf16 v[112:115], v[164:167], v[228:231], v[112:115]
	v_mfma_f32_16x16x32_bf16 v[108:111], v[172:175], v[228:231], v[108:111]
	v_mfma_f32_16x16x32_bf16 v[96:99], v[164:167], v[236:239], v[96:99]
	v_mfma_f32_16x16x32_bf16 v[92:95], v[172:175], v[236:239], v[92:95]
	v_mfma_f32_16x16x32_bf16 v[80:83], v[164:167], v[244:247], v[80:83]
	v_mfma_f32_16x16x32_bf16 v[76:79], v[172:175], v[244:247], v[76:79]
	v_mfma_f32_16x16x32_bf16 v[120:123], v[198:201], v[216:219], v[120:123]
	v_mfma_f32_16x16x32_bf16 v[116:119], v[206:209], v[216:219], v[116:119]
	v_mfma_f32_16x16x32_bf16 v[104:107], v[198:201], v[224:227], v[104:107]
	v_mfma_f32_16x16x32_bf16 v[100:103], v[206:209], v[224:227], v[100:103]
	v_mfma_f32_16x16x32_bf16 v[88:91], v[198:201], v[232:235], v[88:91]
	v_mfma_f32_16x16x32_bf16 v[84:87], v[206:209], v[232:235], v[84:87]
	v_mfma_f32_16x16x32_bf16 v[72:75], v[198:201], v[240:243], v[72:75]
	v_mfma_f32_16x16x32_bf16 v[68:71], v[206:209], v[240:243], v[68:71]
	v_mfma_f32_16x16x32_bf16 v[120:123], v[202:205], v[220:223], v[120:123]
	v_mfma_f32_16x16x32_bf16 v[116:119], v[210:213], v[220:223], v[116:119]
	v_mfma_f32_16x16x32_bf16 v[104:107], v[202:205], v[228:231], v[104:107]
	v_mfma_f32_16x16x32_bf16 v[100:103], v[210:213], v[228:231], v[100:103]
	v_mfma_f32_16x16x32_bf16 v[88:91], v[202:205], v[236:239], v[88:91]
	v_mfma_f32_16x16x32_bf16 v[84:87], v[210:213], v[236:239], v[84:87]
	v_mfma_f32_16x16x32_bf16 v[72:75], v[202:205], v[244:247], v[72:75]
	v_mfma_f32_16x16x32_bf16 v[68:71], v[210:213], v[244:247], v[68:71]
	s_barrier
	s_add_i32 s30, s30, s57
	v_lshl_add_u64 v[176:177], s[12:13], 0, v[138:139]
	s_mov_b32 m0, s30
	ds_read_b128 v[216:219], v163 offset:16384
	ds_read_b128 v[220:223], v163 offset:17408
	ds_read_b128 v[224:227], v163 offset:18432
	ds_read_b128 v[228:231], v163 offset:19456
	ds_read_b128 v[232:235], v163 offset:20480
	ds_read_b128 v[236:239], v163 offset:21504
	ds_read_b128 v[240:243], v163 offset:22528
	ds_read_b128 v[244:247], v163 offset:23552
	global_load_lds_dwordx4 v[176:177], off
	s_add_i32 m0, s30, 0x2000
	s_add_u32 s30, s12, 0x40000
	v_lshl_add_u64 v[248:249], s[12:13], 0, v[142:143]
	s_addc_u32 s31, s13, 0
	s_add_i32 s34, s34, s57
	global_load_lds_dwordx4 v[248:249], off
	v_lshl_add_u64 v[2:3], s[30:31], 0, v[138:139]
	s_mov_b32 m0, s34
	v_lshl_add_u64 v[250:251], s[54:55], 0, v[136:137]
	global_load_lds_dwordx4 v[2:3], off
	v_lshl_add_u64 v[2:3], s[30:31], 0, v[142:143]
	s_add_i32 m0, s34, 0x2000
	v_lshl_add_u64 v[252:253], s[54:55], 0, v[140:141]
	global_load_lds_dwordx4 v[2:3], off
	s_mov_b32 m0, s58
	s_nop 0
	global_load_lds_dwordx4 v[250:251], off
	s_mov_b32 m0, s59
	s_nop 0
	global_load_lds_dwordx4 v[252:253], off
	s_waitcnt vmcnt(8)
	s_waitcnt lgkmcnt(0)
	s_barrier
	s_waitcnt lgkmcnt(0)
	v_mfma_f32_16x16x32_bf16 v[64:67], v[132:135], v[216:219], v[64:67]
	v_mfma_f32_16x16x32_bf16 v[60:63], v[168:171], v[216:219], v[60:63]
	v_mfma_f32_16x16x32_bf16 v[48:51], v[132:135], v[224:227], v[48:51]
	v_mfma_f32_16x16x32_bf16 v[44:47], v[168:171], v[224:227], v[44:47]
	v_mfma_f32_16x16x32_bf16 v[32:35], v[132:135], v[232:235], v[32:35]
	v_mfma_f32_16x16x32_bf16 v[28:31], v[168:171], v[232:235], v[28:31]
	v_mfma_f32_16x16x32_bf16 v[16:19], v[132:135], v[240:243], v[16:19]
	v_mfma_f32_16x16x32_bf16 v[12:15], v[168:171], v[240:243], v[12:15]
	v_mfma_f32_16x16x32_bf16 v[64:67], v[164:167], v[220:223], v[64:67]
	v_mfma_f32_16x16x32_bf16 v[60:63], v[172:175], v[220:223], v[60:63]
	v_mfma_f32_16x16x32_bf16 v[48:51], v[164:167], v[228:231], v[48:51]
	v_mfma_f32_16x16x32_bf16 v[44:47], v[172:175], v[228:231], v[44:47]
	v_mfma_f32_16x16x32_bf16 v[32:35], v[164:167], v[236:239], v[32:35]
	v_mfma_f32_16x16x32_bf16 v[28:31], v[172:175], v[236:239], v[28:31]
	v_mfma_f32_16x16x32_bf16 v[16:19], v[164:167], v[244:247], v[16:19]
	v_mfma_f32_16x16x32_bf16 v[12:15], v[172:175], v[244:247], v[12:15]
	v_mfma_f32_16x16x32_bf16 v[56:59], v[198:201], v[216:219], v[56:59]
	v_mfma_f32_16x16x32_bf16 v[52:55], v[206:209], v[216:219], v[52:55]
	v_mfma_f32_16x16x32_bf16 v[40:43], v[198:201], v[224:227], v[40:43]
	v_mfma_f32_16x16x32_bf16 v[36:39], v[206:209], v[224:227], v[36:39]
	v_mfma_f32_16x16x32_bf16 v[24:27], v[198:201], v[232:235], v[24:27]
	v_mfma_f32_16x16x32_bf16 v[20:23], v[206:209], v[232:235], v[20:23]
	v_mfma_f32_16x16x32_bf16 v[8:11], v[198:201], v[240:243], v[8:11]
	v_mfma_f32_16x16x32_bf16 v[2:5], v[206:209], v[240:243], v[4:7]
	v_mfma_f32_16x16x32_bf16 v[56:59], v[202:205], v[220:223], v[56:59]
	v_mfma_f32_16x16x32_bf16 v[52:55], v[210:213], v[220:223], v[52:55]
	v_mfma_f32_16x16x32_bf16 v[40:43], v[202:205], v[228:231], v[40:43]
	v_mfma_f32_16x16x32_bf16 v[36:39], v[210:213], v[228:231], v[36:39]
	v_mfma_f32_16x16x32_bf16 v[24:27], v[202:205], v[236:239], v[24:27]
	v_mfma_f32_16x16x32_bf16 v[20:23], v[210:213], v[236:239], v[20:23]
	v_mfma_f32_16x16x32_bf16 v[8:11], v[202:205], v[244:247], v[8:11]
	v_mfma_f32_16x16x32_bf16 v[2:5], v[210:213], v[244:247], v[2:5]
	s_barrier
	s_add_i32 s34, 0, 0x18000
	v_add_u32_e32 v0, s34, v160
	s_add_i32 s35, 0, 0x1c000
	ds_read_b128 v[132:135], v0
	ds_read_b128 v[164:167], v0 offset:1024
	ds_read_b128 v[168:171], v0 offset:2048
	ds_read_b128 v[172:175], v0 offset:3072
	v_add_u32_e32 v0, s35, v160
	ds_read_b128 v[198:201], v0
	ds_read_b128 v[202:205], v0 offset:1024
	ds_read_b128 v[206:209], v0 offset:2048
	ds_read_b128 v[210:213], v0 offset:3072
	s_add_u32 s30, s54, 0x40000
	s_addc_u32 s31, s55, 0
	s_mov_b32 m0, s60
	v_lshl_add_u64 v[6:7], s[30:31], 0, v[136:137]
	ds_read_b128 v[216:219], v163 offset:32768
	ds_read_b128 v[220:223], v163 offset:33792
	ds_read_b128 v[224:227], v163 offset:34816
	ds_read_b128 v[228:231], v163 offset:35840
	ds_read_b128 v[232:235], v163 offset:36864
	ds_read_b128 v[236:239], v163 offset:37888
	ds_read_b128 v[240:243], v163 offset:38912
	ds_read_b128 v[244:247], v163 offset:39936
	global_load_lds_dwordx4 v[6:7], off
	v_lshl_add_u64 v[6:7], s[30:31], 0, v[140:141]
	s_mov_b32 m0, s61
	s_nop 0
	global_load_lds_dwordx4 v[6:7], off
	s_waitcnt vmcnt(8)
	s_waitcnt lgkmcnt(0)
	s_barrier
	s_waitcnt lgkmcnt(0)
	v_mfma_f32_16x16x32_bf16 v[128:131], v[132:135], v[216:219], v[128:131]
	v_mfma_f32_16x16x32_bf16 v[124:127], v[168:171], v[216:219], v[124:127]
	v_mfma_f32_16x16x32_bf16 v[112:115], v[132:135], v[224:227], v[112:115]
	v_mfma_f32_16x16x32_bf16 v[108:111], v[168:171], v[224:227], v[108:111]
	v_mfma_f32_16x16x32_bf16 v[96:99], v[132:135], v[232:235], v[96:99]
	v_mfma_f32_16x16x32_bf16 v[92:95], v[168:171], v[232:235], v[92:95]
	v_mfma_f32_16x16x32_bf16 v[80:83], v[132:135], v[240:243], v[80:83]
	v_mfma_f32_16x16x32_bf16 v[76:79], v[168:171], v[240:243], v[76:79]
	v_mfma_f32_16x16x32_bf16 v[128:131], v[164:167], v[220:223], v[128:131]
	v_mfma_f32_16x16x32_bf16 v[124:127], v[172:175], v[220:223], v[124:127]
	v_mfma_f32_16x16x32_bf16 v[112:115], v[164:167], v[228:231], v[112:115]
	v_mfma_f32_16x16x32_bf16 v[108:111], v[172:175], v[228:231], v[108:111]
	v_mfma_f32_16x16x32_bf16 v[96:99], v[164:167], v[236:239], v[96:99]
	v_mfma_f32_16x16x32_bf16 v[92:95], v[172:175], v[236:239], v[92:95]
	v_mfma_f32_16x16x32_bf16 v[80:83], v[164:167], v[244:247], v[80:83]
	v_mfma_f32_16x16x32_bf16 v[76:79], v[172:175], v[244:247], v[76:79]
	v_mfma_f32_16x16x32_bf16 v[120:123], v[198:201], v[216:219], v[120:123]
	v_mfma_f32_16x16x32_bf16 v[116:119], v[206:209], v[216:219], v[116:119]
	v_mfma_f32_16x16x32_bf16 v[104:107], v[198:201], v[224:227], v[104:107]
	v_mfma_f32_16x16x32_bf16 v[100:103], v[206:209], v[224:227], v[100:103]
	v_mfma_f32_16x16x32_bf16 v[88:91], v[198:201], v[232:235], v[88:91]
	v_mfma_f32_16x16x32_bf16 v[84:87], v[206:209], v[232:235], v[84:87]
	v_mfma_f32_16x16x32_bf16 v[72:75], v[198:201], v[240:243], v[72:75]
	v_mfma_f32_16x16x32_bf16 v[68:71], v[206:209], v[240:243], v[68:71]
	v_mfma_f32_16x16x32_bf16 v[120:123], v[202:205], v[220:223], v[120:123]
	v_mfma_f32_16x16x32_bf16 v[116:119], v[210:213], v[220:223], v[116:119]
	v_mfma_f32_16x16x32_bf16 v[104:107], v[202:205], v[228:231], v[104:107]
	v_mfma_f32_16x16x32_bf16 v[100:103], v[210:213], v[228:231], v[100:103]
	v_mfma_f32_16x16x32_bf16 v[88:91], v[202:205], v[236:239], v[88:91]
	v_mfma_f32_16x16x32_bf16 v[84:87], v[210:213], v[236:239], v[84:87]
	v_mfma_f32_16x16x32_bf16 v[72:75], v[202:205], v[244:247], v[72:75]
	v_mfma_f32_16x16x32_bf16 v[68:71], v[210:213], v[244:247], v[68:71]
	s_barrier
	s_add_i32 s30, s34, s57
	v_lshl_add_u64 v[6:7], v[176:177], 0, s[90:91]
	s_mov_b32 m0, s30
	ds_read_b128 v[216:219], v163 offset:49152
	ds_read_b128 v[220:223], v163 offset:50176
	ds_read_b128 v[224:227], v163 offset:51200
	ds_read_b128 v[228:231], v163 offset:52224
	ds_read_b128 v[232:235], v163 offset:53248
	ds_read_b128 v[236:239], v163 offset:54272
	ds_read_b128 v[240:243], v163 offset:55296
	ds_read_b128 v[244:247], v163 offset:56320
	global_load_lds_dwordx4 v[6:7], off
	s_add_i32 m0, s30, 0x2000
	s_add_u32 s12, s12, 0x40080
	v_lshl_add_u64 v[6:7], v[248:249], 0, s[90:91]
	s_addc_u32 s13, s13, 0
	s_add_i32 s30, s35, s57
	global_load_lds_dwordx4 v[6:7], off
	v_lshl_add_u64 v[6:7], s[12:13], 0, v[138:139]
	s_mov_b32 m0, s30
	s_nop 0
	global_load_lds_dwordx4 v[6:7], off
	v_lshl_add_u64 v[6:7], s[12:13], 0, v[142:143]
	s_add_i32 m0, s30, 0x2000
	s_nop 0
	global_load_lds_dwordx4 v[6:7], off
	v_lshl_add_u64 v[6:7], v[250:251], 0, s[90:91]
	s_mov_b32 m0, s64
	s_nop 0
	global_load_lds_dwordx4 v[6:7], off
	v_lshl_add_u64 v[6:7], v[252:253], 0, s[90:91]
	s_mov_b32 m0, s65
	s_nop 0
	global_load_lds_dwordx4 v[6:7], off
	s_waitcnt vmcnt(8)
	s_waitcnt lgkmcnt(0)
	s_barrier
	s_waitcnt lgkmcnt(0)
	v_mfma_f32_16x16x32_bf16 v[64:67], v[132:135], v[216:219], v[64:67]
	v_mfma_f32_16x16x32_bf16 v[60:63], v[168:171], v[216:219], v[60:63]
	v_mfma_f32_16x16x32_bf16 v[48:51], v[132:135], v[224:227], v[48:51]
	v_mfma_f32_16x16x32_bf16 v[44:47], v[168:171], v[224:227], v[44:47]
	v_mfma_f32_16x16x32_bf16 v[32:35], v[132:135], v[232:235], v[32:35]
	v_mfma_f32_16x16x32_bf16 v[28:31], v[168:171], v[232:235], v[28:31]
	v_mfma_f32_16x16x32_bf16 v[16:19], v[132:135], v[240:243], v[16:19]
	v_mfma_f32_16x16x32_bf16 v[12:15], v[168:171], v[240:243], v[12:15]
	v_mfma_f32_16x16x32_bf16 v[64:67], v[164:167], v[220:223], v[64:67]
	v_mfma_f32_16x16x32_bf16 v[60:63], v[172:175], v[220:223], v[60:63]
	v_mfma_f32_16x16x32_bf16 v[48:51], v[164:167], v[228:231], v[48:51]
	v_mfma_f32_16x16x32_bf16 v[44:47], v[172:175], v[228:231], v[44:47]
	v_mfma_f32_16x16x32_bf16 v[32:35], v[164:167], v[236:239], v[32:35]
	v_mfma_f32_16x16x32_bf16 v[28:31], v[172:175], v[236:239], v[28:31]
	v_mfma_f32_16x16x32_bf16 v[16:19], v[164:167], v[244:247], v[16:19]
	v_mfma_f32_16x16x32_bf16 v[12:15], v[172:175], v[244:247], v[12:15]
	v_mfma_f32_16x16x32_bf16 v[56:59], v[198:201], v[216:219], v[56:59]
	v_mfma_f32_16x16x32_bf16 v[52:55], v[206:209], v[216:219], v[52:55]
	v_mfma_f32_16x16x32_bf16 v[40:43], v[198:201], v[224:227], v[40:43]
	v_mfma_f32_16x16x32_bf16 v[36:39], v[206:209], v[224:227], v[36:39]
	v_mfma_f32_16x16x32_bf16 v[24:27], v[198:201], v[232:235], v[24:27]
	v_mfma_f32_16x16x32_bf16 v[20:23], v[206:209], v[232:235], v[20:23]
	v_mfma_f32_16x16x32_bf16 v[6:9], v[198:201], v[240:243], v[8:11]
	v_mfma_f32_16x16x32_bf16 v[2:5], v[206:209], v[240:243], v[2:5]
	v_mfma_f32_16x16x32_bf16 v[56:59], v[202:205], v[220:223], v[56:59]
	v_mfma_f32_16x16x32_bf16 v[52:55], v[210:213], v[220:223], v[52:55]
	v_mfma_f32_16x16x32_bf16 v[40:43], v[202:205], v[228:231], v[40:43]
	v_mfma_f32_16x16x32_bf16 v[36:39], v[210:213], v[228:231], v[36:39]
	v_mfma_f32_16x16x32_bf16 v[24:27], v[202:205], v[236:239], v[24:27]
	v_mfma_f32_16x16x32_bf16 v[20:23], v[210:213], v[236:239], v[20:23]
	v_mfma_f32_16x16x32_bf16 v[8:11], v[202:205], v[244:247], v[6:9]
	v_mfma_f32_16x16x32_bf16 v[4:7], v[210:213], v[244:247], v[2:5]
	s_cmpk_lg_i32 s10, 0x300
	s_cbranch_scc1 .Lp5_noearly
	s_and_b64 vcc, exec, s[8:9]
	s_cbranch_vccnz .Lp5_noearly
	v_add_u32_e32 v132, s29, v147
	v_lshl_add_u32 v2, v158, 3, s28
	v_ashrrev_i32_e32 v133, 31, v132
	v_ashrrev_i32_e32 v3, 31, v2
	v_lshlrev_b64 v[132:133], 12, v[132:133]
	v_lshlrev_b64 v[2:3], 1, v[2:3]
	v_lshl_add_u64 v[2:3], s[92:93], 0, v[2:3]
	v_lshl_add_u64 v[2:3], v[2:3], 0, v[132:133]
	s_mov_b64 s[12:13], 0x10000
	global_load_dwordx4 v[216:219], v[2:3], off
	global_load_dwordx4 v[220:223], v[2:3], off offset:256
	v_lshl_add_u64 v[2:3], v[2:3], 0, s[12:13]
	global_load_dwordx4 v[224:227], v[2:3], off
	global_load_dwordx4 v[228:231], v[2:3], off offset:256
	v_lshl_add_u64 v[2:3], v[2:3], 0, s[12:13]
	global_load_dwordx4 v[232:235], v[2:3], off
	global_load_dwordx4 v[236:239], v[2:3], off offset:256
	v_lshl_add_u64 v[2:3], v[2:3], 0, s[12:13]
	global_load_dwordx4 v[240:243], v[2:3], off
	global_load_dwordx4 v[244:247], v[2:3], off offset:256
	s_mov_b64 s[12:13], 0x50000
	v_lshl_add_u64 v[2:3], v[2:3], 0, s[12:13]
	s_mov_b64 s[12:13], 0x10000
	global_load_dwordx4 v[198:201], v[2:3], off
	global_load_dwordx4 v[202:205], v[2:3], off offset:256
	v_lshl_add_u64 v[2:3], v[2:3], 0, s[12:13]
	global_load_dwordx4 v[206:209], v[2:3], off
	global_load_dwordx4 v[210:213], v[2:3], off offset:256
	v_lshl_add_u64 v[2:3], v[2:3], 0, s[12:13]
	global_load_dwordx4 v[164:167], v[2:3], off
	global_load_dwordx4 v[168:171], v[2:3], off offset:256
	v_lshl_add_u64 v[2:3], v[2:3], 0, s[12:13]
	global_load_dwordx4 v[172:175], v[2:3], off
	global_load_dwordx4 v[132:135], v[2:3], off offset:256

.LBB0_549:
	s_setprio 0
	s_and_b64 vcc, exec, s[8:9]
	s_cbranch_vccz .LBB0_551
	s_barrier

.LBB0_639:
	s_ashr_i32 s49, s48, 31
	s_lshl_b64 s[14:15], s[48:49], 19
	v_readlane_b32 s11, v254, 16
	s_add_u32 s50, s11, s14
	v_readlane_b32 s11, v254, 17
	s_addc_u32 s51, s11, s15
	s_and_b64 s[14:15], s[42:43], exec
	s_cselect_b32 s11, s51, s13
	s_cselect_b32 s14, s50, s12
	s_ashr_i32 s47, s46, 31
	s_lshl_b64 s[24:25], s[46:47], 19
	s_add_u32 s52, s74, s24
	s_addc_u32 s53, s75, s25
	s_and_b64 s[24:25], s[42:43], exec
	s_cselect_b32 s15, s53, s55
	s_cselect_b32 s24, s52, s54
	s_add_u32 s12, s12, 0x40080
	s_addc_u32 s13, s13, 0
	s_add_u32 s25, s54, 0x100
	v_mov_b32_e32 v0, 0
	s_addc_u32 s26, s55, 0
	s_mov_b32 s27, -2
	s_waitcnt lgkmcnt(0)
	v_mov_b64_e32 v[0:1], 0
	v_mov_b64_e32 v[2:3], 0
	v_mov_b64_e32 v[4:5], 0
	v_mov_b64_e32 v[6:7], 0
	v_mov_b64_e32 v[8:9], 0
	v_mov_b64_e32 v[10:11], 0
	v_mov_b64_e32 v[12:13], 0
	v_mov_b64_e32 v[14:15], 0
	v_mov_b64_e32 v[16:17], 0
	v_mov_b64_e32 v[18:19], 0
	v_mov_b64_e32 v[20:21], 0
	v_mov_b64_e32 v[22:23], 0
	v_mov_b64_e32 v[24:25], 0
	v_mov_b64_e32 v[26:27], 0
	v_mov_b64_e32 v[28:29], 0
	v_mov_b64_e32 v[30:31], 0
	v_mov_b64_e32 v[32:33], 0
	v_mov_b64_e32 v[34:35], 0
	v_mov_b64_e32 v[36:37], 0
	v_mov_b64_e32 v[38:39], 0
	v_mov_b64_e32 v[40:41], 0
	v_mov_b64_e32 v[42:43], 0
	v_mov_b64_e32 v[44:45], 0
	v_mov_b64_e32 v[46:47], 0
	v_mov_b64_e32 v[48:49], 0
	v_mov_b64_e32 v[50:51], 0
	v_mov_b64_e32 v[52:53], 0
	v_mov_b64_e32 v[54:55], 0
	v_mov_b64_e32 v[56:57], 0
	v_mov_b64_e32 v[58:59], 0
	v_mov_b64_e32 v[60:61], 0
	v_mov_b64_e32 v[62:63], 0
	v_mov_b64_e32 v[64:65], 0
	v_mov_b64_e32 v[66:67], 0
	v_mov_b64_e32 v[68:69], 0
	v_mov_b64_e32 v[70:71], 0
	v_mov_b64_e32 v[72:73], 0
	v_mov_b64_e32 v[74:75], 0
	v_mov_b64_e32 v[76:77], 0
	v_mov_b64_e32 v[78:79], 0
	v_mov_b64_e32 v[80:81], 0
	v_mov_b64_e32 v[82:83], 0
	v_mov_b64_e32 v[84:85], 0
	v_mov_b64_e32 v[86:87], 0
	v_mov_b64_e32 v[88:89], 0
	v_mov_b64_e32 v[90:91], 0
	v_mov_b64_e32 v[92:93], 0
	v_mov_b64_e32 v[94:95], 0
	v_mov_b64_e32 v[96:97], 0
	v_mov_b64_e32 v[98:99], 0
	v_mov_b64_e32 v[100:101], 0
	v_mov_b64_e32 v[102:103], 0
	v_mov_b64_e32 v[104:105], 0
	v_mov_b64_e32 v[106:107], 0
	v_mov_b64_e32 v[108:109], 0
	v_mov_b64_e32 v[110:111], 0
	v_mov_b64_e32 v[112:113], 0
	v_mov_b64_e32 v[114:115], 0
	v_mov_b64_e32 v[116:117], 0
	v_mov_b64_e32 v[118:119], 0
	v_mov_b64_e32 v[120:121], 0
	v_mov_b64_e32 v[122:123], 0
	v_mov_b64_e32 v[124:125], 0
	v_mov_b64_e32 v[126:127], 0
	s_cmp_eq_u32 s99, 1
	s_cbranch_scc0 .Lprio_LBB0_640
	s_setprio 1
.Lprio_LBB0_640:
	.p2align	8
.LBB0_640:
	ds_read_b128 v[144:147], v153
	ds_read_b128 v[156:159], v153 offset:1024
	ds_read_b128 v[160:163], v153 offset:2048
	ds_read_b128 v[164:167], v153 offset:3072
	ds_read_b128 v[168:171], v154
	ds_read_b128 v[172:175], v154 offset:1024
	ds_read_b128 v[176:179], v154 offset:2048
	ds_read_b128 v[180:183], v154 offset:3072
	s_add_u32 s28, s12, 0xfffc0080
	s_addc_u32 s29, s13, -1
	s_cmp_eq_u32 s27, 12
	s_cselect_b32 s57, s11, s29
	s_cselect_b32 s56, s14, s28
	s_cselect_b32 s55, s15, s26
	s_cselect_b32 s54, s24, s25
	s_add_i32 m0, s19, 0xc000
	ds_read_b128 v[184:187], v155
	ds_read_b128 v[188:191], v155 offset:1024
	ds_read_b128 v[192:195], v155 offset:2048
	ds_read_b128 v[196:199], v155 offset:3072
	ds_read_b128 v[200:203], v155 offset:4096
	ds_read_b128 v[204:207], v155 offset:5120
	ds_read_b128 v[208:211], v155 offset:6144
	ds_read_b128 v[216:219], v155 offset:7168
	global_load_lds_dwordx4 v136, s[12:13]
	s_add_i32 m0, s19, 0xe000
	s_nop 0
	global_load_lds_dwordx4 v138, s[12:13]
	s_waitcnt vmcnt(8)
	s_waitcnt lgkmcnt(0)
	s_barrier
	s_waitcnt lgkmcnt(0)
	v_mfma_f32_16x16x32_bf16 v[124:127], v[144:147], v[184:187], v[124:127]
	v_mfma_f32_16x16x32_bf16 v[120:123], v[160:163], v[184:187], v[120:123]
	v_mfma_f32_16x16x32_bf16 v[108:111], v[144:147], v[192:195], v[108:111]
	v_mfma_f32_16x16x32_bf16 v[104:107], v[160:163], v[192:195], v[104:107]
	v_mfma_f32_16x16x32_bf16 v[92:95], v[144:147], v[200:203], v[92:95]
	v_mfma_f32_16x16x32_bf16 v[88:91], v[160:163], v[200:203], v[88:91]
	v_mfma_f32_16x16x32_bf16 v[76:79], v[144:147], v[208:211], v[76:79]
	v_mfma_f32_16x16x32_bf16 v[72:75], v[160:163], v[208:211], v[72:75]
	v_mfma_f32_16x16x32_bf16 v[124:127], v[156:159], v[188:191], v[124:127]
	v_mfma_f32_16x16x32_bf16 v[120:123], v[164:167], v[188:191], v[120:123]
	v_mfma_f32_16x16x32_bf16 v[108:111], v[156:159], v[196:199], v[108:111]
	v_mfma_f32_16x16x32_bf16 v[104:107], v[164:167], v[196:199], v[104:107]
	v_mfma_f32_16x16x32_bf16 v[92:95], v[156:159], v[204:207], v[92:95]
	v_mfma_f32_16x16x32_bf16 v[88:91], v[164:167], v[204:207], v[88:91]
	v_mfma_f32_16x16x32_bf16 v[76:79], v[156:159], v[216:219], v[76:79]
	v_mfma_f32_16x16x32_bf16 v[72:75], v[164:167], v[216:219], v[72:75]
	v_mfma_f32_16x16x32_bf16 v[116:119], v[168:171], v[184:187], v[116:119]
	v_mfma_f32_16x16x32_bf16 v[112:115], v[176:179], v[184:187], v[112:115]
	v_mfma_f32_16x16x32_bf16 v[100:103], v[168:171], v[192:195], v[100:103]
	v_mfma_f32_16x16x32_bf16 v[96:99], v[176:179], v[192:195], v[96:99]
	v_mfma_f32_16x16x32_bf16 v[84:87], v[168:171], v[200:203], v[84:87]
	v_mfma_f32_16x16x32_bf16 v[80:83], v[176:179], v[200:203], v[80:83]
	v_mfma_f32_16x16x32_bf16 v[68:71], v[168:171], v[208:211], v[68:71]
	v_mfma_f32_16x16x32_bf16 v[64:67], v[176:179], v[208:211], v[64:67]
	v_mfma_f32_16x16x32_bf16 v[116:119], v[172:175], v[188:191], v[116:119]
	v_mfma_f32_16x16x32_bf16 v[112:115], v[180:183], v[188:191], v[112:115]
	v_mfma_f32_16x16x32_bf16 v[100:103], v[172:175], v[196:199], v[100:103]
	v_mfma_f32_16x16x32_bf16 v[96:99], v[180:183], v[196:199], v[96:99]
	v_mfma_f32_16x16x32_bf16 v[84:87], v[172:175], v[204:207], v[84:87]
	v_mfma_f32_16x16x32_bf16 v[80:83], v[180:183], v[204:207], v[80:83]
	v_mfma_f32_16x16x32_bf16 v[68:71], v[172:175], v[216:219], v[68:71]
	v_mfma_f32_16x16x32_bf16 v[64:67], v[180:183], v[216:219], v[64:67]
	s_barrier
	s_add_i32 s28, s63, s18
	s_mov_b32 m0, s28
	ds_read_b128 v[184:187], v155 offset:16384
	ds_read_b128 v[188:191], v155 offset:17408
	ds_read_b128 v[192:195], v155 offset:18432
	ds_read_b128 v[196:199], v155 offset:19456
	ds_read_b128 v[200:203], v155 offset:20480
	ds_read_b128 v[204:207], v155 offset:21504
	ds_read_b128 v[208:211], v155 offset:22528
	ds_read_b128 v[216:219], v155 offset:23552
	global_load_lds_dwordx4 v130, s[54:55]
	s_add_i32 m0, s28, 0x2000
	s_add_u32 s28, s54, 0x40000
	s_addc_u32 s29, s55, 0
	s_add_i32 s30, s64, s18
	global_load_lds_dwordx4 v134, s[54:55]
	s_mov_b32 m0, s30
	s_nop 0
	global_load_lds_dwordx4 v130, s[28:29]
	s_add_i32 m0, s30, 0x2000
	s_nop 0
	global_load_lds_dwordx4 v134, s[28:29]
	s_mov_b32 m0, s19
	s_nop 0
	global_load_lds_dwordx4 v128, s[56:57]
	s_mov_b32 m0, s20
	s_nop 0
	global_load_lds_dwordx4 v132, s[56:57]
	s_waitcnt vmcnt(8)
	s_waitcnt lgkmcnt(0)
	s_barrier
	s_waitcnt lgkmcnt(0)
	v_mfma_f32_16x16x32_bf16 v[60:63], v[144:147], v[184:187], v[60:63]
	v_mfma_f32_16x16x32_bf16 v[56:59], v[160:163], v[184:187], v[56:59]
	v_mfma_f32_16x16x32_bf16 v[44:47], v[144:147], v[192:195], v[44:47]
	v_mfma_f32_16x16x32_bf16 v[40:43], v[160:163], v[192:195], v[40:43]
	v_mfma_f32_16x16x32_bf16 v[28:31], v[144:147], v[200:203], v[28:31]
	v_mfma_f32_16x16x32_bf16 v[24:27], v[160:163], v[200:203], v[24:27]
	v_mfma_f32_16x16x32_bf16 v[12:15], v[144:147], v[208:211], v[12:15]
	v_mfma_f32_16x16x32_bf16 v[8:11], v[160:163], v[208:211], v[8:11]
	v_mfma_f32_16x16x32_bf16 v[60:63], v[156:159], v[188:191], v[60:63]
	v_mfma_f32_16x16x32_bf16 v[56:59], v[164:167], v[188:191], v[56:59]
	v_mfma_f32_16x16x32_bf16 v[44:47], v[156:159], v[196:199], v[44:47]
	v_mfma_f32_16x16x32_bf16 v[40:43], v[164:167], v[196:199], v[40:43]
	v_mfma_f32_16x16x32_bf16 v[28:31], v[156:159], v[204:207], v[28:31]
	v_mfma_f32_16x16x32_bf16 v[24:27], v[164:167], v[204:207], v[24:27]
	v_mfma_f32_16x16x32_bf16 v[12:15], v[156:159], v[216:219], v[12:15]
	v_mfma_f32_16x16x32_bf16 v[8:11], v[164:167], v[216:219], v[8:11]
	v_mfma_f32_16x16x32_bf16 v[52:55], v[168:171], v[184:187], v[52:55]
	v_mfma_f32_16x16x32_bf16 v[48:51], v[176:179], v[184:187], v[48:51]
	v_mfma_f32_16x16x32_bf16 v[36:39], v[168:171], v[192:195], v[36:39]
	v_mfma_f32_16x16x32_bf16 v[32:35], v[176:179], v[192:195], v[32:35]
	v_mfma_f32_16x16x32_bf16 v[20:23], v[168:171], v[200:203], v[20:23]
	v_mfma_f32_16x16x32_bf16 v[16:19], v[176:179], v[200:203], v[16:19]
	v_mfma_f32_16x16x32_bf16 v[4:7], v[168:171], v[208:211], v[4:7]
	v_mfma_f32_16x16x32_bf16 v[0:3], v[176:179], v[208:211], v[0:3]
	v_mfma_f32_16x16x32_bf16 v[52:55], v[172:175], v[188:191], v[52:55]
	v_mfma_f32_16x16x32_bf16 v[48:51], v[180:183], v[188:191], v[48:51]
	v_mfma_f32_16x16x32_bf16 v[36:39], v[172:175], v[196:199], v[36:39]
	v_mfma_f32_16x16x32_bf16 v[32:35], v[180:183], v[196:199], v[32:35]
	v_mfma_f32_16x16x32_bf16 v[20:23], v[172:175], v[204:207], v[20:23]
	v_mfma_f32_16x16x32_bf16 v[16:19], v[180:183], v[204:207], v[16:19]
	v_mfma_f32_16x16x32_bf16 v[4:7], v[172:175], v[216:219], v[4:7]
	v_mfma_f32_16x16x32_bf16 v[0:3], v[180:183], v[216:219], v[0:3]
	s_barrier
	s_add_i32 s30, 0, 0x18000
	s_add_i32 s31, 0, 0x1c000
	v_add_u32_e32 v164, s30, v151
	v_add_u32_e32 v180, s31, v151
	ds_read_b128 v[144:147], v164
	ds_read_b128 v[156:159], v164 offset:1024
	ds_read_b128 v[160:163], v164 offset:2048
	ds_read_b128 v[164:167], v164 offset:3072
	ds_read_b128 v[168:171], v180
	ds_read_b128 v[172:175], v180 offset:1024
	ds_read_b128 v[176:179], v180 offset:2048
	ds_read_b128 v[180:183], v180 offset:3072
	s_add_u32 s28, s56, 0x40000
	s_addc_u32 s29, s57, 0
	s_mov_b32 m0, s21
	ds_read_b128 v[184:187], v155 offset:32768
	ds_read_b128 v[188:191], v155 offset:33792
	ds_read_b128 v[192:195], v155 offset:34816
	ds_read_b128 v[196:199], v155 offset:35840
	ds_read_b128 v[200:203], v155 offset:36864
	ds_read_b128 v[204:207], v155 offset:37888
	ds_read_b128 v[208:211], v155 offset:38912
	ds_read_b128 v[216:219], v155 offset:39936
	global_load_lds_dwordx4 v128, s[28:29]
	s_mov_b32 m0, s22
	s_nop 0
	global_load_lds_dwordx4 v132, s[28:29]
	s_waitcnt vmcnt(8)
	s_waitcnt lgkmcnt(0)
	s_barrier
	s_waitcnt lgkmcnt(0)
	v_mfma_f32_16x16x32_bf16 v[124:127], v[144:147], v[184:187], v[124:127]
	v_mfma_f32_16x16x32_bf16 v[120:123], v[160:163], v[184:187], v[120:123]
	v_mfma_f32_16x16x32_bf16 v[108:111], v[144:147], v[192:195], v[108:111]
	v_mfma_f32_16x16x32_bf16 v[104:107], v[160:163], v[192:195], v[104:107]
	v_mfma_f32_16x16x32_bf16 v[92:95], v[144:147], v[200:203], v[92:95]
	v_mfma_f32_16x16x32_bf16 v[88:91], v[160:163], v[200:203], v[88:91]
	v_mfma_f32_16x16x32_bf16 v[76:79], v[144:147], v[208:211], v[76:79]
	v_mfma_f32_16x16x32_bf16 v[72:75], v[160:163], v[208:211], v[72:75]
	v_mfma_f32_16x16x32_bf16 v[124:127], v[156:159], v[188:191], v[124:127]
	v_mfma_f32_16x16x32_bf16 v[120:123], v[164:167], v[188:191], v[120:123]
	v_mfma_f32_16x16x32_bf16 v[108:111], v[156:159], v[196:199], v[108:111]
	v_mfma_f32_16x16x32_bf16 v[104:107], v[164:167], v[196:199], v[104:107]
	v_mfma_f32_16x16x32_bf16 v[92:95], v[156:159], v[204:207], v[92:95]
	v_mfma_f32_16x16x32_bf16 v[88:91], v[164:167], v[204:207], v[88:91]
	v_mfma_f32_16x16x32_bf16 v[76:79], v[156:159], v[216:219], v[76:79]
	v_mfma_f32_16x16x32_bf16 v[72:75], v[164:167], v[216:219], v[72:75]
	v_mfma_f32_16x16x32_bf16 v[116:119], v[168:171], v[184:187], v[116:119]
	v_mfma_f32_16x16x32_bf16 v[112:115], v[176:179], v[184:187], v[112:115]
	v_mfma_f32_16x16x32_bf16 v[100:103], v[168:171], v[192:195], v[100:103]
	v_mfma_f32_16x16x32_bf16 v[96:99], v[176:179], v[192:195], v[96:99]
	v_mfma_f32_16x16x32_bf16 v[84:87], v[168:171], v[200:203], v[84:87]
	v_mfma_f32_16x16x32_bf16 v[80:83], v[176:179], v[200:203], v[80:83]
	v_mfma_f32_16x16x32_bf16 v[68:71], v[168:171], v[208:211], v[68:71]
	v_mfma_f32_16x16x32_bf16 v[64:67], v[176:179], v[208:211], v[64:67]
	v_mfma_f32_16x16x32_bf16 v[116:119], v[172:175], v[188:191], v[116:119]
	v_mfma_f32_16x16x32_bf16 v[112:115], v[180:183], v[188:191], v[112:115]
	v_mfma_f32_16x16x32_bf16 v[100:103], v[172:175], v[196:199], v[100:103]
	v_mfma_f32_16x16x32_bf16 v[96:99], v[180:183], v[196:199], v[96:99]
	v_mfma_f32_16x16x32_bf16 v[84:87], v[172:175], v[204:207], v[84:87]
	v_mfma_f32_16x16x32_bf16 v[80:83], v[180:183], v[204:207], v[80:83]
	v_mfma_f32_16x16x32_bf16 v[68:71], v[172:175], v[216:219], v[68:71]
	v_mfma_f32_16x16x32_bf16 v[64:67], v[180:183], v[216:219], v[64:67]
	s_barrier
	s_add_i32 m0, s30, s18
	s_add_u32 s28, s54, 0x80
	s_addc_u32 s29, s55, 0
	ds_read_b128 v[184:187], v155 offset:49152
	ds_read_b128 v[188:191], v155 offset:50176
	ds_read_b128 v[192:195], v155 offset:51200
	ds_read_b128 v[196:199], v155 offset:52224
	ds_read_b128 v[200:203], v155 offset:53248
	ds_read_b128 v[204:207], v155 offset:54272
	ds_read_b128 v[208:211], v155 offset:55296
	ds_read_b128 v[216:219], v155 offset:56320
	global_load_lds_dwordx4 v130, s[28:29]
	s_add_i32 m0, m0, 0x2000
	s_add_i32 s30, s31, s18
	global_load_lds_dwordx4 v134, s[28:29]
	s_add_u32 s28, s28, 0x40000
	s_addc_u32 s29, s29, 0
	s_mov_b32 m0, s30
	s_nop 0
	global_load_lds_dwordx4 v130, s[28:29]
	s_add_i32 m0, s30, 0x2000
	s_nop 0
	global_load_lds_dwordx4 v134, s[28:29]
	s_add_u32 s28, s56, 0x80
	s_addc_u32 s29, s57, 0
	s_mov_b32 m0, s33
	s_nop 0
	global_load_lds_dwordx4 v128, s[28:29]
	s_mov_b32 m0, s58
	s_nop 0
	global_load_lds_dwordx4 v132, s[28:29]
	s_add_u32 s28, s54, 0x40080
	s_addc_u32 s29, s55, 0
	s_waitcnt vmcnt(8)
	s_waitcnt lgkmcnt(0)
	s_barrier
	s_waitcnt lgkmcnt(0)
	v_mfma_f32_16x16x32_bf16 v[60:63], v[144:147], v[184:187], v[60:63]
	v_mfma_f32_16x16x32_bf16 v[56:59], v[160:163], v[184:187], v[56:59]
	v_mfma_f32_16x16x32_bf16 v[44:47], v[144:147], v[192:195], v[44:47]
	v_mfma_f32_16x16x32_bf16 v[40:43], v[160:163], v[192:195], v[40:43]
	v_mfma_f32_16x16x32_bf16 v[28:31], v[144:147], v[200:203], v[28:31]
	v_mfma_f32_16x16x32_bf16 v[24:27], v[160:163], v[200:203], v[24:27]
	v_mfma_f32_16x16x32_bf16 v[12:15], v[144:147], v[208:211], v[12:15]
	v_mfma_f32_16x16x32_bf16 v[8:11], v[160:163], v[208:211], v[8:11]
	v_mfma_f32_16x16x32_bf16 v[60:63], v[156:159], v[188:191], v[60:63]
	v_mfma_f32_16x16x32_bf16 v[56:59], v[164:167], v[188:191], v[56:59]
	v_mfma_f32_16x16x32_bf16 v[44:47], v[156:159], v[196:199], v[44:47]
	v_mfma_f32_16x16x32_bf16 v[40:43], v[164:167], v[196:199], v[40:43]
	v_mfma_f32_16x16x32_bf16 v[28:31], v[156:159], v[204:207], v[28:31]
	v_mfma_f32_16x16x32_bf16 v[24:27], v[164:167], v[204:207], v[24:27]
	v_mfma_f32_16x16x32_bf16 v[12:15], v[156:159], v[216:219], v[12:15]
	v_mfma_f32_16x16x32_bf16 v[8:11], v[164:167], v[216:219], v[8:11]
	v_mfma_f32_16x16x32_bf16 v[52:55], v[168:171], v[184:187], v[52:55]
	v_mfma_f32_16x16x32_bf16 v[48:51], v[176:179], v[184:187], v[48:51]
	v_mfma_f32_16x16x32_bf16 v[36:39], v[168:171], v[192:195], v[36:39]
	v_mfma_f32_16x16x32_bf16 v[32:35], v[176:179], v[192:195], v[32:35]
	v_mfma_f32_16x16x32_bf16 v[20:23], v[168:171], v[200:203], v[20:23]
	v_mfma_f32_16x16x32_bf16 v[16:19], v[176:179], v[200:203], v[16:19]
	v_mfma_f32_16x16x32_bf16 v[4:7], v[168:171], v[208:211], v[4:7]
	v_mfma_f32_16x16x32_bf16 v[0:3], v[176:179], v[208:211], v[0:3]
	v_mfma_f32_16x16x32_bf16 v[52:55], v[172:175], v[188:191], v[52:55]
	v_mfma_f32_16x16x32_bf16 v[48:51], v[180:183], v[188:191], v[48:51]
	v_mfma_f32_16x16x32_bf16 v[36:39], v[172:175], v[196:199], v[36:39]
	v_mfma_f32_16x16x32_bf16 v[32:35], v[180:183], v[196:199], v[32:35]
	v_mfma_f32_16x16x32_bf16 v[20:23], v[172:175], v[204:207], v[20:23]
	v_mfma_f32_16x16x32_bf16 v[16:19], v[180:183], v[204:207], v[16:19]
	v_mfma_f32_16x16x32_bf16 v[4:7], v[172:175], v[216:219], v[4:7]
	v_mfma_f32_16x16x32_bf16 v[0:3], v[180:183], v[216:219], v[0:3]
	s_barrier
	s_add_i32 s27, s27, 2
	s_add_u32 s12, s12, 0x100
	s_addc_u32 s13, s13, 0
	s_add_u32 s25, s25, 0x100
	s_addc_u32 s26, s26, 0
	s_cmp_gt_u32 s27, 13
	s_cbranch_scc0 .LBB0_640
	s_setprio 0
	s_and_b64 vcc, exec, s[8:9]
	s_cbranch_vccz .LBB0_643
	s_barrier

.LBB0_743:
	s_ashr_i32 s81, s80, 31
	s_lshl_b64 s[14:15], s[80:81], 19
	s_add_u32 s82, s96, s14
	s_addc_u32 s83, s97, s15
	s_and_b64 s[14:15], s[44:45], exec
	s_cselect_b32 s11, s83, s47
	s_cselect_b32 s14, s82, s46
	s_ashr_i32 s75, s74, 31
	s_lshl_b64 s[16:17], s[74:75], 19
	v_readlane_b32 s24, v254, 6
	v_readlane_b32 s25, v254, 7
	s_add_u32 s84, s24, s16
	s_addc_u32 s85, s25, s17
	s_and_b64 s[16:17], s[44:45], exec
	s_cselect_b32 s15, s85, s49
	s_cselect_b32 s16, s84, s48
	s_add_u32 s46, s46, 0x40080
	s_addc_u32 s47, s47, 0
	s_add_u32 s17, s48, 0x100
	v_mov_b32_e32 v64, 0
	s_addc_u32 s24, s49, 0
	s_mov_b32 s25, -2
	v_mov_b64_e32 v[0:1], 0
	v_mov_b64_e32 v[2:3], 0
	v_mov_b64_e32 v[4:5], 0
	v_mov_b64_e32 v[6:7], 0
	v_mov_b64_e32 v[8:9], 0
	v_mov_b64_e32 v[10:11], 0
	v_mov_b64_e32 v[12:13], 0
	v_mov_b64_e32 v[14:15], 0
	v_mov_b64_e32 v[16:17], 0
	v_mov_b64_e32 v[18:19], 0
	v_mov_b64_e32 v[20:21], 0
	v_mov_b64_e32 v[22:23], 0
	v_mov_b64_e32 v[24:25], 0
	v_mov_b64_e32 v[26:27], 0
	v_mov_b64_e32 v[28:29], 0
	v_mov_b64_e32 v[30:31], 0
	v_mov_b64_e32 v[32:33], 0
	v_mov_b64_e32 v[34:35], 0
	v_mov_b64_e32 v[36:37], 0
	v_mov_b64_e32 v[38:39], 0
	v_mov_b64_e32 v[40:41], 0
	v_mov_b64_e32 v[42:43], 0
	v_mov_b64_e32 v[44:45], 0
	v_mov_b64_e32 v[46:47], 0
	v_mov_b64_e32 v[48:49], 0
	v_mov_b64_e32 v[50:51], 0
	v_mov_b64_e32 v[52:53], 0
	v_mov_b64_e32 v[54:55], 0
	v_mov_b64_e32 v[56:57], 0
	v_mov_b64_e32 v[58:59], 0
	v_mov_b64_e32 v[60:61], 0
	v_mov_b64_e32 v[62:63], 0
	v_mov_b64_e32 v[64:65], 0
	v_mov_b64_e32 v[66:67], 0
	v_mov_b64_e32 v[68:69], 0
	v_mov_b64_e32 v[70:71], 0
	v_mov_b64_e32 v[72:73], 0
	v_mov_b64_e32 v[74:75], 0
	v_mov_b64_e32 v[76:77], 0
	v_mov_b64_e32 v[78:79], 0
	v_mov_b64_e32 v[96:97], 0
	v_mov_b64_e32 v[98:99], 0
	v_mov_b64_e32 v[100:101], 0
	v_mov_b64_e32 v[102:103], 0
	v_mov_b64_e32 v[104:105], 0
	v_mov_b64_e32 v[106:107], 0
	v_mov_b64_e32 v[108:109], 0
	v_mov_b64_e32 v[110:111], 0
	v_mov_b64_e32 v[112:113], 0
	v_mov_b64_e32 v[114:115], 0
	v_mov_b64_e32 v[116:117], 0
	v_mov_b64_e32 v[118:119], 0
	v_mov_b64_e32 v[120:121], 0
	v_mov_b64_e32 v[122:123], 0
	v_mov_b64_e32 v[124:125], 0
	v_mov_b64_e32 v[126:127], 0
	v_mov_b64_e32 v[136:137], 0
	v_mov_b64_e32 v[138:139], 0
	v_mov_b64_e32 v[140:141], 0
	v_mov_b64_e32 v[142:143], 0
	v_mov_b64_e32 v[144:145], 0
	v_mov_b64_e32 v[146:147], 0
	v_mov_b64_e32 v[148:149], 0
	v_mov_b64_e32 v[150:151], 0
	s_cmp_eq_u32 s99, 1
	s_cbranch_scc0 .Lprio_LBB0_744
	s_setprio 1

.LBB0_744:
	ds_read_b128 v[80:83], v226
	ds_read_b128 v[84:87], v226 offset:1024
	ds_read_b128 v[88:91], v226 offset:2048
	ds_read_b128 v[92:95], v226 offset:3072
	ds_read_b128 v[128:131], v227
	ds_read_b128 v[132:135], v227 offset:1024
	ds_read_b128 v[152:155], v227 offset:2048
	ds_read_b128 v[156:159], v227 offset:3072
	s_add_u32 s26, s46, 0xfffc0080
	s_addc_u32 s27, s47, -1
	s_cmp_eq_u32 s25, 12
	s_cselect_b32 s89, s11, s27
	s_cselect_b32 s88, s14, s26
	s_cselect_b32 s49, s15, s24
	s_cselect_b32 s48, s16, s17
	s_add_i32 m0, s13, 0xc000
	ds_read_b128 v[160:163], v228
	ds_read_b128 v[164:167], v228 offset:1024
	ds_read_b128 v[168:171], v228 offset:2048
	ds_read_b128 v[172:175], v228 offset:3072
	ds_read_b128 v[192:195], v228 offset:4096
	ds_read_b128 v[196:199], v228 offset:5120
	ds_read_b128 v[200:203], v228 offset:6144
	ds_read_b128 v[204:207], v228 offset:7168
	global_load_lds_dwordx4 v184, s[46:47]
	s_add_i32 m0, s13, 0xe000
	s_nop 0
	global_load_lds_dwordx4 v186, s[46:47]
	s_waitcnt vmcnt(8)
	s_waitcnt lgkmcnt(0)
	s_barrier
	s_waitcnt lgkmcnt(0)
	v_mfma_f32_16x16x32_bf16 v[76:79], v[80:83], v[160:163], v[76:79]
	v_mfma_f32_16x16x32_bf16 v[64:67], v[88:91], v[160:163], v[64:67]
	v_mfma_f32_16x16x32_bf16 v[148:151], v[80:83], v[168:171], v[148:151]
	v_mfma_f32_16x16x32_bf16 v[140:143], v[88:91], v[168:171], v[140:143]
	v_mfma_f32_16x16x32_bf16 v[124:127], v[80:83], v[192:195], v[124:127]
	v_mfma_f32_16x16x32_bf16 v[120:123], v[88:91], v[192:195], v[120:123]
	v_mfma_f32_16x16x32_bf16 v[72:75], v[80:83], v[200:203], v[72:75]
	v_mfma_f32_16x16x32_bf16 v[60:63], v[88:91], v[200:203], v[60:63]
	v_mfma_f32_16x16x32_bf16 v[76:79], v[84:87], v[164:167], v[76:79]
	v_mfma_f32_16x16x32_bf16 v[64:67], v[92:95], v[164:167], v[64:67]
	v_mfma_f32_16x16x32_bf16 v[148:151], v[84:87], v[172:175], v[148:151]
	v_mfma_f32_16x16x32_bf16 v[140:143], v[92:95], v[172:175], v[140:143]
	v_mfma_f32_16x16x32_bf16 v[124:127], v[84:87], v[196:199], v[124:127]
	v_mfma_f32_16x16x32_bf16 v[120:123], v[92:95], v[196:199], v[120:123]
	v_mfma_f32_16x16x32_bf16 v[72:75], v[84:87], v[204:207], v[72:75]
	v_mfma_f32_16x16x32_bf16 v[60:63], v[92:95], v[204:207], v[60:63]
	v_mfma_f32_16x16x32_bf16 v[144:147], v[128:131], v[160:163], v[144:147]
	v_mfma_f32_16x16x32_bf16 v[136:139], v[152:155], v[160:163], v[136:139]
	v_mfma_f32_16x16x32_bf16 v[116:119], v[128:131], v[168:171], v[116:119]
	v_mfma_f32_16x16x32_bf16 v[112:115], v[152:155], v[168:171], v[112:115]
	v_mfma_f32_16x16x32_bf16 v[108:111], v[128:131], v[192:195], v[108:111]
	v_mfma_f32_16x16x32_bf16 v[104:107], v[152:155], v[192:195], v[104:107]
	v_mfma_f32_16x16x32_bf16 v[100:103], v[128:131], v[200:203], v[100:103]
	v_mfma_f32_16x16x32_bf16 v[96:99], v[152:155], v[200:203], v[96:99]
	v_mfma_f32_16x16x32_bf16 v[144:147], v[132:135], v[164:167], v[144:147]
	v_mfma_f32_16x16x32_bf16 v[136:139], v[156:159], v[164:167], v[136:139]
	v_mfma_f32_16x16x32_bf16 v[116:119], v[132:135], v[172:175], v[116:119]
	v_mfma_f32_16x16x32_bf16 v[112:115], v[156:159], v[172:175], v[112:115]
	v_mfma_f32_16x16x32_bf16 v[108:111], v[132:135], v[196:199], v[108:111]
	v_mfma_f32_16x16x32_bf16 v[104:107], v[156:159], v[196:199], v[104:107]
	v_mfma_f32_16x16x32_bf16 v[100:103], v[132:135], v[204:207], v[100:103]
	v_mfma_f32_16x16x32_bf16 v[96:99], v[156:159], v[204:207], v[96:99]
	s_barrier
	s_add_i32 s26, s3, s20
	s_mov_b32 m0, s26
	ds_read_b128 v[160:163], v228 offset:16384
	ds_read_b128 v[164:167], v228 offset:17408
	ds_read_b128 v[168:171], v228 offset:18432
	ds_read_b128 v[172:175], v228 offset:19456
	ds_read_b128 v[192:195], v228 offset:20480
	ds_read_b128 v[196:199], v228 offset:21504
	ds_read_b128 v[200:203], v228 offset:22528
	ds_read_b128 v[204:207], v228 offset:23552
	global_load_lds_dwordx4 v178, s[48:49]
	s_add_i32 m0, s26, 0x2000
	s_add_u32 s26, s48, 0x40000
	s_addc_u32 s27, s49, 0
	s_add_i32 s28, s93, s20
	global_load_lds_dwordx4 v182, s[48:49]
	s_mov_b32 m0, s28
	s_nop 0
	global_load_lds_dwordx4 v178, s[26:27]
	s_add_i32 m0, s28, 0x2000
	s_nop 0
	global_load_lds_dwordx4 v182, s[26:27]
	s_mov_b32 m0, s13
	s_nop 0
	global_load_lds_dwordx4 v176, s[88:89]
	s_mov_b32 m0, s21
	s_nop 0
	global_load_lds_dwordx4 v180, s[88:89]
	s_waitcnt vmcnt(8)
	s_waitcnt lgkmcnt(0)
	s_barrier
	s_waitcnt lgkmcnt(0)
	v_mfma_f32_16x16x32_bf16 v[68:71], v[80:83], v[160:163], v[68:71]
	v_mfma_f32_16x16x32_bf16 v[36:39], v[88:91], v[160:163], v[36:39]
	v_mfma_f32_16x16x32_bf16 v[52:55], v[80:83], v[168:171], v[52:55]
	v_mfma_f32_16x16x32_bf16 v[44:47], v[88:91], v[168:171], v[44:47]
	v_mfma_f32_16x16x32_bf16 v[28:31], v[80:83], v[192:195], v[28:31]
	v_mfma_f32_16x16x32_bf16 v[24:27], v[88:91], v[192:195], v[24:27]
	v_mfma_f32_16x16x32_bf16 v[56:59], v[80:83], v[200:203], v[56:59]
	v_mfma_f32_16x16x32_bf16 v[32:35], v[88:91], v[200:203], v[32:35]
	v_mfma_f32_16x16x32_bf16 v[68:71], v[84:87], v[164:167], v[68:71]
	v_mfma_f32_16x16x32_bf16 v[36:39], v[92:95], v[164:167], v[36:39]
	v_mfma_f32_16x16x32_bf16 v[52:55], v[84:87], v[172:175], v[52:55]
	v_mfma_f32_16x16x32_bf16 v[44:47], v[92:95], v[172:175], v[44:47]
	v_mfma_f32_16x16x32_bf16 v[28:31], v[84:87], v[196:199], v[28:31]
	v_mfma_f32_16x16x32_bf16 v[24:27], v[92:95], v[196:199], v[24:27]
	v_mfma_f32_16x16x32_bf16 v[56:59], v[84:87], v[204:207], v[56:59]
	v_mfma_f32_16x16x32_bf16 v[32:35], v[92:95], v[204:207], v[32:35]
	v_mfma_f32_16x16x32_bf16 v[48:51], v[128:131], v[160:163], v[48:51]
	v_mfma_f32_16x16x32_bf16 v[40:43], v[152:155], v[160:163], v[40:43]
	v_mfma_f32_16x16x32_bf16 v[20:23], v[128:131], v[168:171], v[20:23]
	v_mfma_f32_16x16x32_bf16 v[16:19], v[152:155], v[168:171], v[16:19]
	v_mfma_f32_16x16x32_bf16 v[12:15], v[128:131], v[192:195], v[12:15]
	v_mfma_f32_16x16x32_bf16 v[8:11], v[152:155], v[192:195], v[8:11]
	v_mfma_f32_16x16x32_bf16 v[4:7], v[128:131], v[200:203], v[4:7]
	v_mfma_f32_16x16x32_bf16 v[0:3], v[152:155], v[200:203], v[0:3]
	v_mfma_f32_16x16x32_bf16 v[48:51], v[132:135], v[164:167], v[48:51]
	v_mfma_f32_16x16x32_bf16 v[40:43], v[156:159], v[164:167], v[40:43]
	v_mfma_f32_16x16x32_bf16 v[20:23], v[132:135], v[172:175], v[20:23]
	v_mfma_f32_16x16x32_bf16 v[16:19], v[156:159], v[172:175], v[16:19]
	v_mfma_f32_16x16x32_bf16 v[12:15], v[132:135], v[196:199], v[12:15]
	v_mfma_f32_16x16x32_bf16 v[8:11], v[156:159], v[196:199], v[8:11]
	v_mfma_f32_16x16x32_bf16 v[4:7], v[132:135], v[204:207], v[4:7]
	v_mfma_f32_16x16x32_bf16 v[0:3], v[156:159], v[204:207], v[0:3]
	s_barrier
	s_add_i32 s28, 0, 0x18000
	s_add_i32 s29, 0, 0x1c000
	v_add_u32_e32 v92, s28, v218
	v_add_u32_e32 v156, s29, v218
	ds_read_b128 v[80:83], v92
	ds_read_b128 v[84:87], v92 offset:1024
	ds_read_b128 v[88:91], v92 offset:2048
	ds_read_b128 v[92:95], v92 offset:3072
	ds_read_b128 v[128:131], v156
	ds_read_b128 v[132:135], v156 offset:1024
	ds_read_b128 v[152:155], v156 offset:2048
	ds_read_b128 v[156:159], v156 offset:3072
	s_add_u32 s26, s88, 0x40000
	s_addc_u32 s27, s89, 0
	s_mov_b32 m0, s22
	ds_read_b128 v[160:163], v228 offset:32768
	ds_read_b128 v[164:167], v228 offset:33792
	ds_read_b128 v[168:171], v228 offset:34816
	ds_read_b128 v[172:175], v228 offset:35840
	ds_read_b128 v[192:195], v228 offset:36864
	ds_read_b128 v[196:199], v228 offset:37888
	ds_read_b128 v[200:203], v228 offset:38912
	ds_read_b128 v[204:207], v228 offset:39936
	global_load_lds_dwordx4 v176, s[26:27]
	s_mov_b32 m0, s23
	s_nop 0
	global_load_lds_dwordx4 v180, s[26:27]
	s_waitcnt vmcnt(8)
	s_waitcnt lgkmcnt(0)
	s_barrier
	s_waitcnt lgkmcnt(0)
	v_mfma_f32_16x16x32_bf16 v[76:79], v[80:83], v[160:163], v[76:79]
	v_mfma_f32_16x16x32_bf16 v[64:67], v[88:91], v[160:163], v[64:67]
	v_mfma_f32_16x16x32_bf16 v[148:151], v[80:83], v[168:171], v[148:151]
	v_mfma_f32_16x16x32_bf16 v[140:143], v[88:91], v[168:171], v[140:143]
	v_mfma_f32_16x16x32_bf16 v[124:127], v[80:83], v[192:195], v[124:127]
	v_mfma_f32_16x16x32_bf16 v[120:123], v[88:91], v[192:195], v[120:123]
	v_mfma_f32_16x16x32_bf16 v[72:75], v[80:83], v[200:203], v[72:75]
	v_mfma_f32_16x16x32_bf16 v[60:63], v[88:91], v[200:203], v[60:63]
	v_mfma_f32_16x16x32_bf16 v[76:79], v[84:87], v[164:167], v[76:79]
	v_mfma_f32_16x16x32_bf16 v[64:67], v[92:95], v[164:167], v[64:67]
	v_mfma_f32_16x16x32_bf16 v[148:151], v[84:87], v[172:175], v[148:151]
	v_mfma_f32_16x16x32_bf16 v[140:143], v[92:95], v[172:175], v[140:143]
	v_mfma_f32_16x16x32_bf16 v[124:127], v[84:87], v[196:199], v[124:127]
	v_mfma_f32_16x16x32_bf16 v[120:123], v[92:95], v[196:199], v[120:123]
	v_mfma_f32_16x16x32_bf16 v[72:75], v[84:87], v[204:207], v[72:75]
	v_mfma_f32_16x16x32_bf16 v[60:63], v[92:95], v[204:207], v[60:63]
	v_mfma_f32_16x16x32_bf16 v[144:147], v[128:131], v[160:163], v[144:147]
	v_mfma_f32_16x16x32_bf16 v[136:139], v[152:155], v[160:163], v[136:139]
	v_mfma_f32_16x16x32_bf16 v[116:119], v[128:131], v[168:171], v[116:119]
	v_mfma_f32_16x16x32_bf16 v[112:115], v[152:155], v[168:171], v[112:115]
	v_mfma_f32_16x16x32_bf16 v[108:111], v[128:131], v[192:195], v[108:111]
	v_mfma_f32_16x16x32_bf16 v[104:107], v[152:155], v[192:195], v[104:107]
	v_mfma_f32_16x16x32_bf16 v[100:103], v[128:131], v[200:203], v[100:103]
	v_mfma_f32_16x16x32_bf16 v[96:99], v[152:155], v[200:203], v[96:99]
	v_mfma_f32_16x16x32_bf16 v[144:147], v[132:135], v[164:167], v[144:147]
	v_mfma_f32_16x16x32_bf16 v[136:139], v[156:159], v[164:167], v[136:139]
	v_mfma_f32_16x16x32_bf16 v[116:119], v[132:135], v[172:175], v[116:119]
	v_mfma_f32_16x16x32_bf16 v[112:115], v[156:159], v[172:175], v[112:115]
	v_mfma_f32_16x16x32_bf16 v[108:111], v[132:135], v[196:199], v[108:111]
	v_mfma_f32_16x16x32_bf16 v[104:107], v[156:159], v[196:199], v[104:107]
	v_mfma_f32_16x16x32_bf16 v[100:103], v[132:135], v[204:207], v[100:103]
	v_mfma_f32_16x16x32_bf16 v[96:99], v[156:159], v[204:207], v[96:99]
	s_barrier
	s_add_i32 m0, s28, s20
	s_add_u32 s26, s48, 0x80
	s_addc_u32 s27, s49, 0
	ds_read_b128 v[160:163], v228 offset:49152
	ds_read_b128 v[164:167], v228 offset:50176
	ds_read_b128 v[168:171], v228 offset:51200
	ds_read_b128 v[172:175], v228 offset:52224
	ds_read_b128 v[192:195], v228 offset:53248
	ds_read_b128 v[196:199], v228 offset:54272
	ds_read_b128 v[200:203], v228 offset:55296
	ds_read_b128 v[204:207], v228 offset:56320
	global_load_lds_dwordx4 v178, s[26:27]
	s_add_i32 m0, m0, 0x2000
	s_add_i32 s28, s29, s20
	global_load_lds_dwordx4 v182, s[26:27]
	s_add_u32 s26, s26, 0x40000
	s_addc_u32 s27, s27, 0
	s_mov_b32 m0, s28
	s_nop 0
	global_load_lds_dwordx4 v178, s[26:27]
	s_add_i32 m0, s28, 0x2000
	s_nop 0
	global_load_lds_dwordx4 v182, s[26:27]
	s_add_u32 s26, s88, 0x80
	s_addc_u32 s27, s89, 0
	s_mov_b32 m0, s71
	s_nop 0
	global_load_lds_dwordx4 v176, s[26:27]
	s_mov_b32 m0, s73
	s_nop 0
	global_load_lds_dwordx4 v180, s[26:27]
	s_add_u32 s26, s48, 0x40080
	s_addc_u32 s27, s49, 0
	s_waitcnt vmcnt(8)
	s_waitcnt lgkmcnt(0)
	s_barrier
	s_waitcnt lgkmcnt(0)
	v_mfma_f32_16x16x32_bf16 v[68:71], v[80:83], v[160:163], v[68:71]
	v_mfma_f32_16x16x32_bf16 v[36:39], v[88:91], v[160:163], v[36:39]
	v_mfma_f32_16x16x32_bf16 v[52:55], v[80:83], v[168:171], v[52:55]
	v_mfma_f32_16x16x32_bf16 v[44:47], v[88:91], v[168:171], v[44:47]
	v_mfma_f32_16x16x32_bf16 v[28:31], v[80:83], v[192:195], v[28:31]
	v_mfma_f32_16x16x32_bf16 v[24:27], v[88:91], v[192:195], v[24:27]
	v_mfma_f32_16x16x32_bf16 v[56:59], v[80:83], v[200:203], v[56:59]
	v_mfma_f32_16x16x32_bf16 v[32:35], v[88:91], v[200:203], v[32:35]
	v_mfma_f32_16x16x32_bf16 v[68:71], v[84:87], v[164:167], v[68:71]
	v_mfma_f32_16x16x32_bf16 v[36:39], v[92:95], v[164:167], v[36:39]
	v_mfma_f32_16x16x32_bf16 v[52:55], v[84:87], v[172:175], v[52:55]
	v_mfma_f32_16x16x32_bf16 v[44:47], v[92:95], v[172:175], v[44:47]
	v_mfma_f32_16x16x32_bf16 v[28:31], v[84:87], v[196:199], v[28:31]
	v_mfma_f32_16x16x32_bf16 v[24:27], v[92:95], v[196:199], v[24:27]
	v_mfma_f32_16x16x32_bf16 v[56:59], v[84:87], v[204:207], v[56:59]
	v_mfma_f32_16x16x32_bf16 v[32:35], v[92:95], v[204:207], v[32:35]
	v_mfma_f32_16x16x32_bf16 v[48:51], v[128:131], v[160:163], v[48:51]
	v_mfma_f32_16x16x32_bf16 v[40:43], v[152:155], v[160:163], v[40:43]
	v_mfma_f32_16x16x32_bf16 v[20:23], v[128:131], v[168:171], v[20:23]
	v_mfma_f32_16x16x32_bf16 v[16:19], v[152:155], v[168:171], v[16:19]
	v_mfma_f32_16x16x32_bf16 v[12:15], v[128:131], v[192:195], v[12:15]
	v_mfma_f32_16x16x32_bf16 v[8:11], v[152:155], v[192:195], v[8:11]
	v_mfma_f32_16x16x32_bf16 v[4:7], v[128:131], v[200:203], v[4:7]
	v_mfma_f32_16x16x32_bf16 v[0:3], v[152:155], v[200:203], v[0:3]
	v_mfma_f32_16x16x32_bf16 v[48:51], v[132:135], v[164:167], v[48:51]
	v_mfma_f32_16x16x32_bf16 v[40:43], v[156:159], v[164:167], v[40:43]
	v_mfma_f32_16x16x32_bf16 v[20:23], v[132:135], v[172:175], v[20:23]
	v_mfma_f32_16x16x32_bf16 v[16:19], v[156:159], v[172:175], v[16:19]
	v_mfma_f32_16x16x32_bf16 v[12:15], v[132:135], v[196:199], v[12:15]
	v_mfma_f32_16x16x32_bf16 v[8:11], v[156:159], v[196:199], v[8:11]
	v_mfma_f32_16x16x32_bf16 v[4:7], v[132:135], v[204:207], v[4:7]
	v_mfma_f32_16x16x32_bf16 v[0:3], v[156:159], v[204:207], v[0:3]
	s_barrier
	s_add_i32 s25, s25, 2
	s_add_u32 s46, s46, 0x100
	s_addc_u32 s47, s47, 0
	s_add_u32 s17, s17, 0x100
	s_addc_u32 s24, s24, 0
	s_cmp_gt_u32 s25, 13
	s_cbranch_scc0 .LBB0_744
	s_setprio 0
	v_mov_b32_e32 v80, v214
	s_movk_i32 s14, 0x100
	s_lshl_b32 s11, s10, 8
	s_nop 0
	s_cmp_eq_u32 s10, s98
	s_cbranch_scc1 .Lp8_rsl_keep1
	v_cmp_gt_i32_e32 vcc, s14, v80
	s_and_saveexec_b64 s[46:47], vcc
	s_cbranch_execz .Lp8_noss
	v_add_u32_e32 v82, s11, v80
	v_ashrrev_i32_e32 v83, 31, v82
	v_lshlrev_b64 v[82:83], 6, v[82:83]
	v_lshl_add_u64 v[94:95], s[0:1], 0, v[82:83]
	global_load_dwordx4 v[82:85], v[94:95], off
	global_load_dwordx4 v[86:89], v[94:95], off offset:16
	global_load_dwordx4 v[90:93], v[94:95], off offset:32
	global_load_dwordx4 v[128:131], v[94:95], off offset:48

.LBB0_954:
	s_add_u32 s13, s46, 0x100
	v_mov_b32_e32 v0, 0
	s_addc_u32 s14, s47, 0
	s_mov_b32 s15, -2
	v_mov_b64_e32 v[0:1], 0
	v_mov_b64_e32 v[2:3], 0
	v_mov_b64_e32 v[4:5], 0
	v_mov_b64_e32 v[6:7], 0
	v_mov_b64_e32 v[8:9], 0
	v_mov_b64_e32 v[10:11], 0
	v_mov_b64_e32 v[12:13], 0
	v_mov_b64_e32 v[14:15], 0
	v_mov_b64_e32 v[16:17], 0
	v_mov_b64_e32 v[18:19], 0
	v_mov_b64_e32 v[20:21], 0
	v_mov_b64_e32 v[22:23], 0
	v_mov_b64_e32 v[24:25], 0
	v_mov_b64_e32 v[26:27], 0
	v_mov_b64_e32 v[28:29], 0
	v_mov_b64_e32 v[30:31], 0
	v_mov_b64_e32 v[32:33], 0
	v_mov_b64_e32 v[34:35], 0
	v_mov_b64_e32 v[36:37], 0
	v_mov_b64_e32 v[38:39], 0
	v_mov_b64_e32 v[40:41], 0
	v_mov_b64_e32 v[42:43], 0
	v_mov_b64_e32 v[44:45], 0
	v_mov_b64_e32 v[46:47], 0
	v_mov_b64_e32 v[48:49], 0
	v_mov_b64_e32 v[50:51], 0
	v_mov_b64_e32 v[52:53], 0
	v_mov_b64_e32 v[54:55], 0
	v_mov_b64_e32 v[56:57], 0
	v_mov_b64_e32 v[58:59], 0
	v_mov_b64_e32 v[60:61], 0
	v_mov_b64_e32 v[62:63], 0
	v_mov_b64_e32 v[64:65], 0
	v_mov_b64_e32 v[66:67], 0
	v_mov_b64_e32 v[68:69], 0
	v_mov_b64_e32 v[70:71], 0
	v_mov_b64_e32 v[72:73], 0
	v_mov_b64_e32 v[74:75], 0
	v_mov_b64_e32 v[76:77], 0
	v_mov_b64_e32 v[78:79], 0
	v_mov_b64_e32 v[80:81], 0
	v_mov_b64_e32 v[82:83], 0
	v_mov_b64_e32 v[84:85], 0
	v_mov_b64_e32 v[86:87], 0
	v_mov_b64_e32 v[88:89], 0
	v_mov_b64_e32 v[90:91], 0
	v_mov_b64_e32 v[92:93], 0
	v_mov_b64_e32 v[94:95], 0
	v_mov_b64_e32 v[96:97], 0
	v_mov_b64_e32 v[98:99], 0
	v_mov_b64_e32 v[100:101], 0
	v_mov_b64_e32 v[102:103], 0
	v_mov_b64_e32 v[104:105], 0
	v_mov_b64_e32 v[106:107], 0
	v_mov_b64_e32 v[108:109], 0
	v_mov_b64_e32 v[110:111], 0
	v_mov_b64_e32 v[112:113], 0
	v_mov_b64_e32 v[114:115], 0
	v_mov_b64_e32 v[116:117], 0
	v_mov_b64_e32 v[118:119], 0
	v_mov_b64_e32 v[120:121], 0
	v_mov_b64_e32 v[122:123], 0
	v_mov_b64_e32 v[124:125], 0
	v_mov_b64_e32 v[126:127], 0
	s_cmp_eq_u32 s99, 1
	s_cbranch_scc0 .Lprio_LBB0_955
	s_setprio 1

.LBB0_955:
	ds_read_b128 v[128:131], v197
	ds_read_b128 v[132:135], v197 offset:1024
	ds_read_b128 v[136:139], v197 offset:2048
	ds_read_b128 v[140:143], v197 offset:3072
	ds_read_b128 v[144:147], v198
	ds_read_b128 v[148:151], v198 offset:1024
	ds_read_b128 v[168:171], v198 offset:2048
	ds_read_b128 v[172:175], v198 offset:3072
	s_add_u32 s42, s44, 0x100
	s_addc_u32 s43, s45, 0
	s_cmp_eq_u32 s15, 40
	s_cselect_b32 s53, s9, s43
	s_cselect_b32 s52, s8, s42
	s_cselect_b32 s47, s11, s14
	s_cselect_b32 s46, s10, s13
	v_lshl_add_u64 v[176:177], s[44:45], 0, v[160:161]
	s_add_i32 m0, s18, 0xc000
	ds_read_b128 v[202:205], v199
	ds_read_b128 v[206:209], v199 offset:1024
	ds_read_b128 v[210:213], v199 offset:2048
	ds_read_b128 v[216:219], v199 offset:3072
	ds_read_b128 v[220:223], v199 offset:4096
	ds_read_b128 v[224:227], v199 offset:5120
	ds_read_b128 v[228:231], v199 offset:6144
	ds_read_b128 v[232:235], v199 offset:7168
	global_load_lds_dwordx4 v[176:177], off
	v_lshl_add_u64 v[176:177], s[44:45], 0, v[162:163]
	s_add_i32 m0, s18, 0xe000
	s_nop 0
	global_load_lds_dwordx4 v[176:177], off
	s_waitcnt vmcnt(8)
	s_waitcnt lgkmcnt(0)
	s_barrier
	s_waitcnt lgkmcnt(0)
	v_mfma_f32_16x16x32_bf16 v[124:127], v[128:131], v[202:205], v[124:127]
	v_mfma_f32_16x16x32_bf16 v[120:123], v[136:139], v[202:205], v[120:123]
	v_mfma_f32_16x16x32_bf16 v[108:111], v[128:131], v[210:213], v[108:111]
	v_mfma_f32_16x16x32_bf16 v[104:107], v[136:139], v[210:213], v[104:107]
	v_mfma_f32_16x16x32_bf16 v[92:95], v[128:131], v[220:223], v[92:95]
	v_mfma_f32_16x16x32_bf16 v[88:91], v[136:139], v[220:223], v[88:91]
	v_mfma_f32_16x16x32_bf16 v[76:79], v[128:131], v[228:231], v[76:79]
	v_mfma_f32_16x16x32_bf16 v[72:75], v[136:139], v[228:231], v[72:75]
	v_mfma_f32_16x16x32_bf16 v[124:127], v[132:135], v[206:209], v[124:127]
	v_mfma_f32_16x16x32_bf16 v[120:123], v[140:143], v[206:209], v[120:123]
	v_mfma_f32_16x16x32_bf16 v[108:111], v[132:135], v[216:219], v[108:111]
	v_mfma_f32_16x16x32_bf16 v[104:107], v[140:143], v[216:219], v[104:107]
	v_mfma_f32_16x16x32_bf16 v[92:95], v[132:135], v[224:227], v[92:95]
	v_mfma_f32_16x16x32_bf16 v[88:91], v[140:143], v[224:227], v[88:91]
	v_mfma_f32_16x16x32_bf16 v[76:79], v[132:135], v[232:235], v[76:79]
	v_mfma_f32_16x16x32_bf16 v[72:75], v[140:143], v[232:235], v[72:75]
	v_mfma_f32_16x16x32_bf16 v[116:119], v[144:147], v[202:205], v[116:119]
	v_mfma_f32_16x16x32_bf16 v[112:115], v[168:171], v[202:205], v[112:115]
	v_mfma_f32_16x16x32_bf16 v[100:103], v[144:147], v[210:213], v[100:103]
	v_mfma_f32_16x16x32_bf16 v[96:99], v[168:171], v[210:213], v[96:99]
	v_mfma_f32_16x16x32_bf16 v[84:87], v[144:147], v[220:223], v[84:87]
	v_mfma_f32_16x16x32_bf16 v[80:83], v[168:171], v[220:223], v[80:83]
	v_mfma_f32_16x16x32_bf16 v[68:71], v[144:147], v[228:231], v[68:71]
	v_mfma_f32_16x16x32_bf16 v[64:67], v[168:171], v[228:231], v[64:67]
	v_mfma_f32_16x16x32_bf16 v[116:119], v[148:151], v[206:209], v[116:119]
	v_mfma_f32_16x16x32_bf16 v[112:115], v[172:175], v[206:209], v[112:115]
	v_mfma_f32_16x16x32_bf16 v[100:103], v[148:151], v[216:219], v[100:103]
	v_mfma_f32_16x16x32_bf16 v[96:99], v[172:175], v[216:219], v[96:99]
	v_mfma_f32_16x16x32_bf16 v[84:87], v[148:151], v[224:227], v[84:87]
	v_mfma_f32_16x16x32_bf16 v[80:83], v[172:175], v[224:227], v[80:83]
	v_mfma_f32_16x16x32_bf16 v[68:71], v[148:151], v[232:235], v[68:71]
	v_mfma_f32_16x16x32_bf16 v[64:67], v[172:175], v[232:235], v[64:67]
	s_barrier
	s_add_i32 s30, s54, s17
	s_mov_b32 m0, s30
	ds_read_b128 v[202:205], v199 offset:16384
	ds_read_b128 v[206:209], v199 offset:17408
	ds_read_b128 v[210:213], v199 offset:18432
	ds_read_b128 v[216:219], v199 offset:19456
	ds_read_b128 v[220:223], v199 offset:20480
	ds_read_b128 v[224:227], v199 offset:21504
	ds_read_b128 v[228:231], v199 offset:22528
	ds_read_b128 v[232:235], v199 offset:23552
	global_load_lds_dwordx4 v154, s[46:47]
	s_add_i32 m0, s30, 0x2000
	s_add_u32 s30, s46, 0xb0000
	s_addc_u32 s31, s47, 0
	s_add_i32 s34, s55, s17
	global_load_lds_dwordx4 v158, s[46:47]
	s_mov_b32 m0, s34
	s_nop 0
	global_load_lds_dwordx4 v154, s[30:31]
	s_add_i32 m0, s34, 0x2000
	s_nop 0
	global_load_lds_dwordx4 v158, s[30:31]
	s_mov_b32 m0, s18
	s_nop 0
	global_load_lds_dwordx4 v152, s[52:53]
	s_mov_b32 m0, s19
	s_nop 0
	global_load_lds_dwordx4 v156, s[52:53]
	s_waitcnt vmcnt(8)
	s_waitcnt lgkmcnt(0)
	s_barrier
	s_waitcnt lgkmcnt(0)
	v_mfma_f32_16x16x32_bf16 v[60:63], v[128:131], v[202:205], v[60:63]
	v_mfma_f32_16x16x32_bf16 v[56:59], v[136:139], v[202:205], v[56:59]
	v_mfma_f32_16x16x32_bf16 v[44:47], v[128:131], v[210:213], v[44:47]
	v_mfma_f32_16x16x32_bf16 v[40:43], v[136:139], v[210:213], v[40:43]
	v_mfma_f32_16x16x32_bf16 v[28:31], v[128:131], v[220:223], v[28:31]
	v_mfma_f32_16x16x32_bf16 v[24:27], v[136:139], v[220:223], v[24:27]
	v_mfma_f32_16x16x32_bf16 v[12:15], v[128:131], v[228:231], v[12:15]
	v_mfma_f32_16x16x32_bf16 v[8:11], v[136:139], v[228:231], v[8:11]
	v_mfma_f32_16x16x32_bf16 v[60:63], v[132:135], v[206:209], v[60:63]
	v_mfma_f32_16x16x32_bf16 v[56:59], v[140:143], v[206:209], v[56:59]
	v_mfma_f32_16x16x32_bf16 v[44:47], v[132:135], v[216:219], v[44:47]
	v_mfma_f32_16x16x32_bf16 v[40:43], v[140:143], v[216:219], v[40:43]
	v_mfma_f32_16x16x32_bf16 v[28:31], v[132:135], v[224:227], v[28:31]
	v_mfma_f32_16x16x32_bf16 v[24:27], v[140:143], v[224:227], v[24:27]
	v_mfma_f32_16x16x32_bf16 v[12:15], v[132:135], v[232:235], v[12:15]
	v_mfma_f32_16x16x32_bf16 v[8:11], v[140:143], v[232:235], v[8:11]
	v_mfma_f32_16x16x32_bf16 v[52:55], v[144:147], v[202:205], v[52:55]
	v_mfma_f32_16x16x32_bf16 v[48:51], v[168:171], v[202:205], v[48:51]
	v_mfma_f32_16x16x32_bf16 v[36:39], v[144:147], v[210:213], v[36:39]
	v_mfma_f32_16x16x32_bf16 v[32:35], v[168:171], v[210:213], v[32:35]
	v_mfma_f32_16x16x32_bf16 v[20:23], v[144:147], v[220:223], v[20:23]
	v_mfma_f32_16x16x32_bf16 v[16:19], v[168:171], v[220:223], v[16:19]
	v_mfma_f32_16x16x32_bf16 v[4:7], v[144:147], v[228:231], v[4:7]
	v_mfma_f32_16x16x32_bf16 v[0:3], v[168:171], v[228:231], v[0:3]
	v_mfma_f32_16x16x32_bf16 v[52:55], v[148:151], v[206:209], v[52:55]
	v_mfma_f32_16x16x32_bf16 v[48:51], v[172:175], v[206:209], v[48:51]
	v_mfma_f32_16x16x32_bf16 v[36:39], v[148:151], v[216:219], v[36:39]
	v_mfma_f32_16x16x32_bf16 v[32:35], v[172:175], v[216:219], v[32:35]
	v_mfma_f32_16x16x32_bf16 v[20:23], v[148:151], v[224:227], v[20:23]
	v_mfma_f32_16x16x32_bf16 v[16:19], v[172:175], v[224:227], v[16:19]
	v_mfma_f32_16x16x32_bf16 v[4:7], v[148:151], v[232:235], v[4:7]
	v_mfma_f32_16x16x32_bf16 v[0:3], v[172:175], v[232:235], v[0:3]
	s_barrier
	s_add_i32 s34, 0, 0x18000
	s_add_i32 s35, 0, 0x1c000
	v_add_u32_e32 v140, s34, v180
	v_add_u32_e32 v172, s35, v180
	ds_read_b128 v[128:131], v140
	ds_read_b128 v[132:135], v140 offset:1024
	ds_read_b128 v[136:139], v140 offset:2048
	ds_read_b128 v[140:143], v140 offset:3072
	ds_read_b128 v[144:147], v172
	ds_read_b128 v[148:151], v172 offset:1024
	ds_read_b128 v[168:171], v172 offset:2048
	ds_read_b128 v[172:175], v172 offset:3072
	s_add_u32 s30, s52, 0xb0000
	s_addc_u32 s31, s53, 0
	s_mov_b32 m0, s20
	ds_read_b128 v[202:205], v199 offset:32768
	ds_read_b128 v[206:209], v199 offset:33792
	ds_read_b128 v[210:213], v199 offset:34816
	ds_read_b128 v[216:219], v199 offset:35840
	ds_read_b128 v[220:223], v199 offset:36864
	ds_read_b128 v[224:227], v199 offset:37888
	ds_read_b128 v[228:231], v199 offset:38912
	ds_read_b128 v[232:235], v199 offset:39936
	global_load_lds_dwordx4 v152, s[30:31]
	s_mov_b32 m0, s21
	s_nop 0
	global_load_lds_dwordx4 v156, s[30:31]
	s_waitcnt vmcnt(8)
	s_waitcnt lgkmcnt(0)
	s_barrier
	s_waitcnt lgkmcnt(0)
	v_mfma_f32_16x16x32_bf16 v[124:127], v[128:131], v[202:205], v[124:127]
	v_mfma_f32_16x16x32_bf16 v[120:123], v[136:139], v[202:205], v[120:123]
	v_mfma_f32_16x16x32_bf16 v[108:111], v[128:131], v[210:213], v[108:111]
	v_mfma_f32_16x16x32_bf16 v[104:107], v[136:139], v[210:213], v[104:107]
	v_mfma_f32_16x16x32_bf16 v[92:95], v[128:131], v[220:223], v[92:95]
	v_mfma_f32_16x16x32_bf16 v[88:91], v[136:139], v[220:223], v[88:91]
	v_mfma_f32_16x16x32_bf16 v[76:79], v[128:131], v[228:231], v[76:79]
	v_mfma_f32_16x16x32_bf16 v[72:75], v[136:139], v[228:231], v[72:75]
	v_mfma_f32_16x16x32_bf16 v[124:127], v[132:135], v[206:209], v[124:127]
	v_mfma_f32_16x16x32_bf16 v[120:123], v[140:143], v[206:209], v[120:123]
	v_mfma_f32_16x16x32_bf16 v[108:111], v[132:135], v[216:219], v[108:111]
	v_mfma_f32_16x16x32_bf16 v[104:107], v[140:143], v[216:219], v[104:107]
	v_mfma_f32_16x16x32_bf16 v[92:95], v[132:135], v[224:227], v[92:95]
	v_mfma_f32_16x16x32_bf16 v[88:91], v[140:143], v[224:227], v[88:91]
	v_mfma_f32_16x16x32_bf16 v[76:79], v[132:135], v[232:235], v[76:79]
	v_mfma_f32_16x16x32_bf16 v[72:75], v[140:143], v[232:235], v[72:75]
	v_mfma_f32_16x16x32_bf16 v[116:119], v[144:147], v[202:205], v[116:119]
	v_mfma_f32_16x16x32_bf16 v[112:115], v[168:171], v[202:205], v[112:115]
	v_mfma_f32_16x16x32_bf16 v[100:103], v[144:147], v[210:213], v[100:103]
	v_mfma_f32_16x16x32_bf16 v[96:99], v[168:171], v[210:213], v[96:99]
	v_mfma_f32_16x16x32_bf16 v[84:87], v[144:147], v[220:223], v[84:87]
	v_mfma_f32_16x16x32_bf16 v[80:83], v[168:171], v[220:223], v[80:83]
	v_mfma_f32_16x16x32_bf16 v[68:71], v[144:147], v[228:231], v[68:71]
	v_mfma_f32_16x16x32_bf16 v[64:67], v[168:171], v[228:231], v[64:67]
	v_mfma_f32_16x16x32_bf16 v[116:119], v[148:151], v[206:209], v[116:119]
	v_mfma_f32_16x16x32_bf16 v[112:115], v[172:175], v[206:209], v[112:115]
	v_mfma_f32_16x16x32_bf16 v[100:103], v[148:151], v[216:219], v[100:103]
	v_mfma_f32_16x16x32_bf16 v[96:99], v[172:175], v[216:219], v[96:99]
	v_mfma_f32_16x16x32_bf16 v[84:87], v[148:151], v[224:227], v[84:87]
	v_mfma_f32_16x16x32_bf16 v[80:83], v[172:175], v[224:227], v[80:83]
	v_mfma_f32_16x16x32_bf16 v[68:71], v[148:151], v[232:235], v[68:71]
	v_mfma_f32_16x16x32_bf16 v[64:67], v[172:175], v[232:235], v[64:67]
	s_barrier
	s_add_i32 m0, s34, s17
	s_add_u32 s30, s46, 0x80
	s_addc_u32 s31, s47, 0
	ds_read_b128 v[202:205], v199 offset:49152
	ds_read_b128 v[206:209], v199 offset:50176
	ds_read_b128 v[210:213], v199 offset:51200
	ds_read_b128 v[216:219], v199 offset:52224
	ds_read_b128 v[220:223], v199 offset:53248
	ds_read_b128 v[224:227], v199 offset:54272
	ds_read_b128 v[228:231], v199 offset:55296
	ds_read_b128 v[232:235], v199 offset:56320
	global_load_lds_dwordx4 v154, s[30:31]
	s_add_i32 m0, m0, 0x2000
	s_add_i32 s34, s35, s17
	global_load_lds_dwordx4 v158, s[30:31]
	s_add_u32 s30, s30, 0xb0000
	s_addc_u32 s31, s31, 0
	s_mov_b32 m0, s34
	s_nop 0
	global_load_lds_dwordx4 v154, s[30:31]
	s_add_i32 m0, s34, 0x2000
	s_nop 0
	global_load_lds_dwordx4 v158, s[30:31]
	s_add_u32 s30, s52, 0x80
	s_addc_u32 s31, s53, 0
	s_mov_b32 m0, s25
	s_nop 0
	global_load_lds_dwordx4 v152, s[30:31]
	s_mov_b32 m0, s26
	s_nop 0
	global_load_lds_dwordx4 v156, s[30:31]
	s_add_u32 s30, s46, 0xb0080
	s_addc_u32 s31, s47, 0
	s_waitcnt vmcnt(8)
	s_waitcnt lgkmcnt(0)
	s_barrier
	s_waitcnt lgkmcnt(0)
	v_mfma_f32_16x16x32_bf16 v[60:63], v[128:131], v[202:205], v[60:63]
	v_mfma_f32_16x16x32_bf16 v[56:59], v[136:139], v[202:205], v[56:59]
	v_mfma_f32_16x16x32_bf16 v[44:47], v[128:131], v[210:213], v[44:47]
	v_mfma_f32_16x16x32_bf16 v[40:43], v[136:139], v[210:213], v[40:43]
	v_mfma_f32_16x16x32_bf16 v[28:31], v[128:131], v[220:223], v[28:31]
	v_mfma_f32_16x16x32_bf16 v[24:27], v[136:139], v[220:223], v[24:27]
	v_mfma_f32_16x16x32_bf16 v[12:15], v[128:131], v[228:231], v[12:15]
	v_mfma_f32_16x16x32_bf16 v[8:11], v[136:139], v[228:231], v[8:11]
	v_mfma_f32_16x16x32_bf16 v[60:63], v[132:135], v[206:209], v[60:63]
	v_mfma_f32_16x16x32_bf16 v[56:59], v[140:143], v[206:209], v[56:59]
	v_mfma_f32_16x16x32_bf16 v[44:47], v[132:135], v[216:219], v[44:47]
	v_mfma_f32_16x16x32_bf16 v[40:43], v[140:143], v[216:219], v[40:43]
	v_mfma_f32_16x16x32_bf16 v[28:31], v[132:135], v[224:227], v[28:31]
	v_mfma_f32_16x16x32_bf16 v[24:27], v[140:143], v[224:227], v[24:27]
	v_mfma_f32_16x16x32_bf16 v[12:15], v[132:135], v[232:235], v[12:15]
	v_mfma_f32_16x16x32_bf16 v[8:11], v[140:143], v[232:235], v[8:11]
	v_mfma_f32_16x16x32_bf16 v[52:55], v[144:147], v[202:205], v[52:55]
	v_mfma_f32_16x16x32_bf16 v[48:51], v[168:171], v[202:205], v[48:51]
	v_mfma_f32_16x16x32_bf16 v[36:39], v[144:147], v[210:213], v[36:39]
	v_mfma_f32_16x16x32_bf16 v[32:35], v[168:171], v[210:213], v[32:35]
	v_mfma_f32_16x16x32_bf16 v[20:23], v[144:147], v[220:223], v[20:23]
	v_mfma_f32_16x16x32_bf16 v[16:19], v[168:171], v[220:223], v[16:19]
	v_mfma_f32_16x16x32_bf16 v[4:7], v[144:147], v[228:231], v[4:7]
	v_mfma_f32_16x16x32_bf16 v[0:3], v[168:171], v[228:231], v[0:3]
	v_mfma_f32_16x16x32_bf16 v[52:55], v[148:151], v[206:209], v[52:55]
	v_mfma_f32_16x16x32_bf16 v[48:51], v[172:175], v[206:209], v[48:51]
	v_mfma_f32_16x16x32_bf16 v[36:39], v[148:151], v[216:219], v[36:39]
	v_mfma_f32_16x16x32_bf16 v[32:35], v[172:175], v[216:219], v[32:35]
	v_mfma_f32_16x16x32_bf16 v[20:23], v[148:151], v[224:227], v[20:23]
	v_mfma_f32_16x16x32_bf16 v[16:19], v[172:175], v[224:227], v[16:19]
	v_mfma_f32_16x16x32_bf16 v[4:7], v[148:151], v[232:235], v[4:7]
	v_mfma_f32_16x16x32_bf16 v[0:3], v[172:175], v[232:235], v[0:3]
	s_barrier
	s_add_i32 s15, s15, 2
	s_add_u32 s13, s13, 0x100
	s_addc_u32 s14, s14, 0
	s_cmp_gt_u32 s15, 41
	s_mov_b64 s[44:45], s[42:43]
	s_cbranch_scc0 .LBB0_955
	s_setprio 0
	s_and_b64 vcc, exec, s[6:7]
	s_cbranch_vccz .LBB0_958
	s_barrier
